# stack of small latency trims on the best: DPP top-k merge (ph10), batched query loads (ph9), permlane/DPP reductions in modulate loops, live conversion-stream loops and ph3 epilogue
# speedup vs baseline: 1.0070x; 1.0039x over previous
.LBB0_259:
	v_lshl_add_u64 v[114:115], v[56:57], 0, s[14:15]
	global_load_dwordx4 v[98:101], v[114:115], off offset:16 nt
	global_load_dwordx4 v[102:105], v[114:115], off nt
	global_load_dwordx4 v[106:109], v[114:115], off offset:2064 nt
	global_load_dwordx4 v[110:113], v[114:115], off offset:2048 nt
	v_add_co_u32_e32 v122, vcc, s19, v114
	v_lshl_add_u64 v[118:119], v[114:115], 0, s[10:11]
	v_lshl_add_u64 v[126:127], v[114:115], 0, s[12:13]
	v_addc_co_u32_e32 v123, vcc, 0, v115, vcc
	global_load_dwordx4 v[114:117], v[122:123], off nt
	s_nop 0
	global_load_dwordx4 v[118:121], v[118:119], off offset:16 nt
	s_nop 0
	global_load_dwordx4 v[122:125], v[122:123], off offset:2048 nt
	s_nop 0
	global_load_dwordx4 v[126:129], v[126:127], off offset:16 nt
	s_add_u32 s14, s14, 0x2000
	s_addc_u32 s15, s15, 0
	s_cmp_eq_u32 s14, 0x10000
	s_waitcnt vmcnt(6)
	v_mul_f32_e32 v45, v103, v103
	v_fmac_f32_e32 v45, v102, v102
	v_fmac_f32_e32 v45, v104, v104
	v_fmac_f32_e32 v45, v105, v105
	v_fmac_f32_e32 v45, v98, v98
	v_fmac_f32_e32 v45, v99, v99
	v_fmac_f32_e32 v45, v100, v100
	v_fmac_f32_e32 v45, v101, v101
	s_waitcnt vmcnt(4)
	v_fmac_f32_e32 v45, v110, v110
	v_fmac_f32_e32 v45, v111, v111
	v_fmac_f32_e32 v45, v112, v112
	v_fmac_f32_e32 v45, v113, v113
	v_fmac_f32_e32 v45, v106, v106
	v_fmac_f32_e32 v45, v107, v107
	v_fmac_f32_e32 v45, v108, v108
	v_fmac_f32_e32 v45, v109, v109
	s_waitcnt vmcnt(3)
	v_fmac_f32_e32 v45, v114, v114
	v_fmac_f32_e32 v45, v115, v115
	v_fmac_f32_e32 v45, v116, v116
	v_fmac_f32_e32 v45, v117, v117
	s_waitcnt vmcnt(2)
	v_fmac_f32_e32 v45, v118, v118
	v_fmac_f32_e32 v45, v119, v119
	v_fmac_f32_e32 v45, v120, v120
	v_fmac_f32_e32 v45, v121, v121
	s_waitcnt vmcnt(1)
	v_fmac_f32_e32 v45, v122, v122
	v_fmac_f32_e32 v45, v123, v123
	v_fmac_f32_e32 v45, v124, v124
	v_fmac_f32_e32 v45, v125, v125
	s_waitcnt vmcnt(0)
	v_fmac_f32_e32 v45, v126, v126
	v_pk_mul_f32 v[130:131], v[128:129], v[128:129]
	v_fmac_f32_e32 v45, v127, v127
	v_add_f32_e32 v45, v130, v45
	v_add_f32_e32 v45, v131, v45
	v_mov_b32_e32 v97, v45
	s_nop 1
	v_permlane32_swap_b32_e32 v97, v45
	v_add_f32_e32 v45, v45, v97
	v_mov_b32_e32 v97, v45
	s_nop 1
	v_permlane16_swap_b32_e32 v97, v45
	v_add_f32_e32 v45, v45, v97
	s_nop 1
	v_add_f32_dpp v45, v45, v45 row_ror:8 row_mask:0xf bank_mask:0xf
	s_nop 1
	v_add_f32_dpp v45, v45, v45 row_ror:4 row_mask:0xf bank_mask:0xf
	s_nop 1
	v_add_f32_dpp v45, v45, v45 row_ror:2 row_mask:0xf bank_mask:0xf
	s_nop 1
	v_add_f32_dpp v45, v45, v45 row_ror:1 row_mask:0xf bank_mask:0xf
	v_fmamk_f32 v45, v45, 0x3a000000, v96
	v_rsq_f32_e32 v130, v45
	s_nop 0
	v_pk_mul_f32 v[102:103], v[102:103], v[130:131] op_sel_hi:[1,0]
	v_pk_mul_f32 v[104:105], v[104:105], v[130:131] op_sel_hi:[1,0]
	v_pk_mul_f32 v[98:99], v[98:99], v[130:131] op_sel_hi:[1,0]
	v_pk_mul_f32 v[100:101], v[100:101], v[130:131] op_sel_hi:[1,0]
	v_pk_mul_f32 v[110:111], v[110:111], v[130:131] op_sel_hi:[1,0]
	v_pk_mul_f32 v[112:113], v[112:113], v[130:131] op_sel_hi:[1,0]
	v_pk_mul_f32 v[106:107], v[106:107], v[130:131] op_sel_hi:[1,0]
	v_pk_mul_f32 v[108:109], v[108:109], v[130:131] op_sel_hi:[1,0]
	v_pk_mul_f32 v[114:115], v[114:115], v[130:131] op_sel_hi:[1,0]
	v_pk_mul_f32 v[116:117], v[116:117], v[130:131] op_sel_hi:[1,0]
	v_pk_mul_f32 v[118:119], v[118:119], v[130:131] op_sel_hi:[1,0]
	v_pk_mul_f32 v[120:121], v[120:121], v[130:131] op_sel_hi:[1,0]
	v_pk_mul_f32 v[122:123], v[122:123], v[130:131] op_sel_hi:[1,0]
	v_pk_mul_f32 v[124:125], v[124:125], v[130:131] op_sel_hi:[1,0]
	v_pk_mul_f32 v[126:127], v[126:127], v[130:131] op_sel_hi:[1,0]
	v_pk_mul_f32 v[128:129], v[128:129], v[130:131] op_sel_hi:[1,0]
	v_pk_fma_f32 v[104:105], v[58:59], v[104:105], v[8:9]
	v_pk_fma_f32 v[102:103], v[60:61], v[102:103], v[6:7]
	v_pk_fma_f32 v[130:131], v[62:63], v[100:101], v[4:5]
	v_pk_fma_f32 v[100:101], v[64:65], v[98:99], v[2:3]
	v_pk_fma_f32 v[112:113], v[66:67], v[112:113], v[16:17]
	v_pk_fma_f32 v[110:111], v[68:69], v[110:111], v[14:15]
	v_pk_fma_f32 v[108:109], v[70:71], v[108:109], v[12:13]
	v_pk_fma_f32 v[106:107], v[72:73], v[106:107], v[10:11]
	v_pk_fma_f32 v[116:117], v[74:75], v[116:117], v[24:25]
	v_pk_fma_f32 v[114:115], v[76:77], v[114:115], v[22:23]
	v_pk_fma_f32 v[120:121], v[78:79], v[120:121], v[20:21]
	v_pk_fma_f32 v[118:119], v[80:81], v[118:119], v[18:19]
	v_pk_fma_f32 v[124:125], v[82:83], v[124:125], v[32:33]
	v_pk_fma_f32 v[122:123], v[84:85], v[122:123], v[30:31]
	v_pk_fma_f32 v[128:129], v[86:87], v[128:129], v[28:29]
	v_pk_fma_f32 v[126:127], v[88:89], v[126:127], v[26:27]
	v_cvt_pk_bf16_f32 v98, v102, v103
	v_cvt_pk_bf16_f32 v99, v104, v105
	v_cvt_pk_bf16_f32 v100, v100, v101
	v_cvt_pk_bf16_f32 v101, v130, v131
	v_cvt_pk_bf16_f32 v102, v110, v111
	v_cvt_pk_bf16_f32 v103, v112, v113
	v_cvt_pk_bf16_f32 v104, v106, v107
	v_cvt_pk_bf16_f32 v105, v108, v109
	v_cvt_pk_bf16_f32 v106, v114, v115
	v_cvt_pk_bf16_f32 v107, v116, v117
	v_cvt_pk_bf16_f32 v108, v118, v119
	v_cvt_pk_bf16_f32 v109, v120, v121
	v_cvt_pk_bf16_f32 v110, v122, v123
	v_cvt_pk_bf16_f32 v111, v124, v125
	v_cvt_pk_bf16_f32 v112, v126, v127
	v_cvt_pk_bf16_f32 v113, v128, v129
	global_store_dwordx4 v[54:55], v[98:101], off
	global_store_dwordx4 v[54:55], v[102:105], off offset:1024
	global_store_dwordx4 v[54:55], v[106:109], off offset:2048
	global_store_dwordx4 v[54:55], v[110:113], off offset:3072
	v_lshl_add_u64 v[54:55], v[54:55], 0, s[10:11]
	s_cbranch_scc0 .LBB0_259
	v_add_u32_e32 v1, s16, v1
	v_cmp_lt_i32_e32 vcc, s20, v1
	s_or_b64 s[6:7], vcc, s[6:7]
	v_add_u32_e32 v44, s18, v44
	s_andn2_b64 exec, exec, s[6:7]
	s_cbranch_execnz .LBB0_258

.LBB0_342:
	ds_read_b128 v[130:133], v182
	ds_read_b128 v[156:159], v182 offset:1024
	ds_read_b128 v[160:163], v182 offset:2048
	ds_read_b128 v[164:167], v182 offset:3072
	s_add_u32 s8, s6, 0xfff80080
	s_addc_u32 s9, s7, -1
	s_cmp_eq_u32 s39, 28
	s_cselect_b32 s11, s1, s9
	s_cselect_b32 s10, s3, s8
	s_cselect_b32 s9, s12, s38
	s_cselect_b32 s8, s13, s16
	v_lshl_add_u64 v[172:173], s[6:7], 0, v[148:149]
	s_add_i32 m0, s86, 0xc000
	ds_read_b128 v[168:171], v183
	ds_read_b128 v[190:193], v183 offset:1024
	ds_read_b128 v[194:197], v183 offset:2048
	ds_read_b128 v[198:201], v183 offset:3072
	ds_read_b128 v[202:205], v183 offset:4096
	ds_read_b128 v[206:209], v183 offset:5120
	ds_read_b128 v[210:213], v183 offset:6144
	ds_read_b128 v[214:217], v183 offset:7168
	global_load_lds_dwordx4 v[172:173], off
	v_lshl_add_u64 v[172:173], s[6:7], 0, v[150:151]
	s_add_i32 m0, s86, 0xe000
	s_nop 0
	global_load_lds_dwordx4 v[172:173], off
	s_waitcnt lgkmcnt(8)
	s_barrier
	s_waitcnt lgkmcnt(0)
	s_setprio 1
	s_waitcnt lgkmcnt(0)
	v_mfma_f32_16x16x32_bf16 v[126:129], v[130:133], v[168:171], v[126:129]
	v_mfma_f32_16x16x32_bf16 v[122:125], v[160:163], v[168:171], v[122:125]
	v_mfma_f32_16x16x32_bf16 v[110:113], v[130:133], v[194:197], v[110:113]
	v_mfma_f32_16x16x32_bf16 v[106:109], v[160:163], v[194:197], v[106:109]
	v_mfma_f32_16x16x32_bf16 v[94:97], v[130:133], v[202:205], v[94:97]
	v_mfma_f32_16x16x32_bf16 v[90:93], v[160:163], v[202:205], v[90:93]
	v_mfma_f32_16x16x32_bf16 v[78:81], v[130:133], v[210:213], v[78:81]
	v_mfma_f32_16x16x32_bf16 v[74:77], v[160:163], v[210:213], v[74:77]
	v_mfma_f32_16x16x32_bf16 v[126:129], v[156:159], v[190:193], v[126:129]
	v_mfma_f32_16x16x32_bf16 v[122:125], v[164:167], v[190:193], v[122:125]
	v_mfma_f32_16x16x32_bf16 v[110:113], v[156:159], v[198:201], v[110:113]
	v_mfma_f32_16x16x32_bf16 v[106:109], v[164:167], v[198:201], v[106:109]
	v_mfma_f32_16x16x32_bf16 v[94:97], v[156:159], v[206:209], v[94:97]
	v_mfma_f32_16x16x32_bf16 v[90:93], v[164:167], v[206:209], v[90:93]
	v_mfma_f32_16x16x32_bf16 v[78:81], v[156:159], v[214:217], v[78:81]
	v_mfma_f32_16x16x32_bf16 v[74:77], v[164:167], v[214:217], v[74:77]
	s_setprio 0
	s_barrier
	s_add_i32 s45, s31, s71
	v_lshl_add_u64 v[172:173], s[8:9], 0, v[134:135]
	s_mov_b32 m0, s45
	ds_read_b128 v[218:221], v184
	ds_read_b128 v[222:225], v184 offset:1024
	ds_read_b128 v[226:229], v184 offset:2048
	ds_read_b128 v[230:233], v184 offset:3072
	global_load_lds_dwordx4 v[172:173], off
	v_lshl_add_u64 v[234:235], s[8:9], 0, v[136:137]
	s_add_i32 m0, s45, 0x2000
	s_nop 0
	global_load_lds_dwordx4 v[234:235], off
	s_barrier
	s_waitcnt lgkmcnt(0)
	s_setprio 1
	s_waitcnt lgkmcnt(0)
	v_mfma_f32_16x16x32_bf16 v[118:121], v[218:221], v[168:171], v[118:121]
	v_mfma_f32_16x16x32_bf16 v[114:117], v[226:229], v[168:171], v[114:117]
	v_mfma_f32_16x16x32_bf16 v[102:105], v[218:221], v[194:197], v[102:105]
	v_mfma_f32_16x16x32_bf16 v[98:101], v[226:229], v[194:197], v[98:101]
	v_mfma_f32_16x16x32_bf16 v[86:89], v[218:221], v[202:205], v[86:89]
	v_mfma_f32_16x16x32_bf16 v[82:85], v[226:229], v[202:205], v[82:85]
	v_mfma_f32_16x16x32_bf16 v[70:73], v[218:221], v[210:213], v[70:73]
	v_mfma_f32_16x16x32_bf16 v[66:69], v[226:229], v[210:213], v[66:69]
	v_mfma_f32_16x16x32_bf16 v[118:121], v[222:225], v[190:193], v[118:121]
	v_mfma_f32_16x16x32_bf16 v[114:117], v[230:233], v[190:193], v[114:117]
	v_mfma_f32_16x16x32_bf16 v[102:105], v[222:225], v[198:201], v[102:105]
	v_mfma_f32_16x16x32_bf16 v[98:101], v[230:233], v[198:201], v[98:101]
	v_mfma_f32_16x16x32_bf16 v[86:89], v[222:225], v[206:209], v[86:89]
	v_mfma_f32_16x16x32_bf16 v[82:85], v[230:233], v[206:209], v[82:85]
	v_mfma_f32_16x16x32_bf16 v[70:73], v[222:225], v[214:217], v[70:73]
	v_mfma_f32_16x16x32_bf16 v[66:69], v[230:233], v[214:217], v[66:69]
	s_setprio 0
	s_mov_b32 m0, s86
	v_lshl_add_u64 v[236:237], s[10:11], 0, v[134:135]
	s_barrier
	ds_read_b128 v[168:171], v183 offset:16384
	ds_read_b128 v[190:193], v183 offset:17408
	ds_read_b128 v[194:197], v183 offset:18432
	ds_read_b128 v[198:201], v183 offset:19456
	ds_read_b128 v[202:205], v183 offset:20480
	ds_read_b128 v[206:209], v183 offset:21504
	ds_read_b128 v[210:213], v183 offset:22528
	ds_read_b128 v[214:217], v183 offset:23552
	global_load_lds_dwordx4 v[236:237], off
	v_lshl_add_u64 v[238:239], s[10:11], 0, v[136:137]
	s_mov_b32 m0, s87
	s_nop 0
	global_load_lds_dwordx4 v[238:239], off
	s_barrier
	s_waitcnt lgkmcnt(0)
	s_setprio 1
	s_waitcnt lgkmcnt(0)
	v_mfma_f32_16x16x32_bf16 v[62:65], v[130:133], v[168:171], v[62:65]
	v_mfma_f32_16x16x32_bf16 v[58:61], v[160:163], v[168:171], v[58:61]
	v_mfma_f32_16x16x32_bf16 v[46:49], v[130:133], v[194:197], v[46:49]
	v_mfma_f32_16x16x32_bf16 v[42:45], v[160:163], v[194:197], v[42:45]
	v_mfma_f32_16x16x32_bf16 v[30:33], v[130:133], v[202:205], v[30:33]
	v_mfma_f32_16x16x32_bf16 v[26:29], v[160:163], v[202:205], v[26:29]
	v_mfma_f32_16x16x32_bf16 v[14:17], v[130:133], v[210:213], v[14:17]
	v_mfma_f32_16x16x32_bf16 v[10:13], v[160:163], v[210:213], v[10:13]
	v_mfma_f32_16x16x32_bf16 v[62:65], v[156:159], v[190:193], v[62:65]
	v_mfma_f32_16x16x32_bf16 v[58:61], v[164:167], v[190:193], v[58:61]
	v_mfma_f32_16x16x32_bf16 v[46:49], v[156:159], v[198:201], v[46:49]
	v_mfma_f32_16x16x32_bf16 v[42:45], v[164:167], v[198:201], v[42:45]
	v_mfma_f32_16x16x32_bf16 v[30:33], v[156:159], v[206:209], v[30:33]
	v_mfma_f32_16x16x32_bf16 v[26:29], v[164:167], v[206:209], v[26:29]
	v_mfma_f32_16x16x32_bf16 v[14:17], v[156:159], v[214:217], v[14:17]
	v_mfma_f32_16x16x32_bf16 v[10:13], v[164:167], v[214:217], v[10:13]
	s_setprio 0
	s_barrier
	s_add_u32 s52, s8, 0x80000
	s_addc_u32 s53, s9, 0
	s_add_i32 s45, s36, s71
	v_lshl_add_u64 v[130:131], s[52:53], 0, v[134:135]
	s_mov_b32 m0, s45
	s_nop 0
	global_load_lds_dwordx4 v[130:131], off
	v_lshl_add_u64 v[130:131], s[52:53], 0, v[136:137]
	s_add_i32 m0, s45, 0x2000
	s_nop 0
	global_load_lds_dwordx4 v[130:131], off
	s_waitcnt vmcnt(6)
	s_barrier
	s_setprio 1
	v_mfma_f32_16x16x32_bf16 v[54:57], v[218:221], v[168:171], v[54:57]
	v_mfma_f32_16x16x32_bf16 v[50:53], v[226:229], v[168:171], v[50:53]
	v_mfma_f32_16x16x32_bf16 v[38:41], v[218:221], v[194:197], v[38:41]
	v_mfma_f32_16x16x32_bf16 v[34:37], v[226:229], v[194:197], v[34:37]
	v_mfma_f32_16x16x32_bf16 v[22:25], v[218:221], v[202:205], v[22:25]
	v_mfma_f32_16x16x32_bf16 v[18:21], v[226:229], v[202:205], v[18:21]
	v_mfma_f32_16x16x32_bf16 v[6:9], v[218:221], v[210:213], v[6:9]
	v_mfma_f32_16x16x32_bf16 v[2:5], v[226:229], v[210:213], v[2:5]
	v_mfma_f32_16x16x32_bf16 v[54:57], v[222:225], v[190:193], v[54:57]
	v_mfma_f32_16x16x32_bf16 v[50:53], v[230:233], v[190:193], v[50:53]
	v_mfma_f32_16x16x32_bf16 v[38:41], v[222:225], v[198:201], v[38:41]
	v_mfma_f32_16x16x32_bf16 v[34:37], v[230:233], v[198:201], v[34:37]
	v_mfma_f32_16x16x32_bf16 v[22:25], v[222:225], v[206:209], v[22:25]
	v_mfma_f32_16x16x32_bf16 v[18:21], v[230:233], v[206:209], v[18:21]
	v_mfma_f32_16x16x32_bf16 v[6:9], v[222:225], v[214:217], v[6:9]
	v_mfma_f32_16x16x32_bf16 v[2:5], v[230:233], v[214:217], v[2:5]
	s_setprio 0
	s_add_i32 s45, 0, 0x18000
	v_add_u32_e32 v138, s45, v141
	s_barrier
	ds_read_b128 v[130:133], v138
	ds_read_b128 v[156:159], v138 offset:1024
	ds_read_b128 v[160:163], v138 offset:2048
	ds_read_b128 v[164:167], v138 offset:3072
	s_add_u32 s10, s10, 0x80000
	s_addc_u32 s11, s11, 0
	s_mov_b32 m0, s96
	v_lshl_add_u64 v[218:219], s[10:11], 0, v[134:135]
	ds_read_b128 v[168:171], v183 offset:32768
	ds_read_b128 v[190:193], v183 offset:33792
	ds_read_b128 v[194:197], v183 offset:34816
	ds_read_b128 v[198:201], v183 offset:35840
	ds_read_b128 v[202:205], v183 offset:36864
	ds_read_b128 v[206:209], v183 offset:37888
	ds_read_b128 v[210:213], v183 offset:38912
	ds_read_b128 v[214:217], v183 offset:39936
	global_load_lds_dwordx4 v[218:219], off
	v_lshl_add_u64 v[218:219], s[10:11], 0, v[136:137]
	s_mov_b32 m0, s97
	s_nop 0
	global_load_lds_dwordx4 v[218:219], off
	s_waitcnt lgkmcnt(8)
	s_barrier
	s_waitcnt lgkmcnt(0)
	s_setprio 1
	s_waitcnt lgkmcnt(0)
	v_mfma_f32_16x16x32_bf16 v[126:129], v[130:133], v[168:171], v[126:129]
	v_mfma_f32_16x16x32_bf16 v[122:125], v[160:163], v[168:171], v[122:125]
	v_mfma_f32_16x16x32_bf16 v[110:113], v[130:133], v[194:197], v[110:113]
	v_mfma_f32_16x16x32_bf16 v[106:109], v[160:163], v[194:197], v[106:109]
	v_mfma_f32_16x16x32_bf16 v[94:97], v[130:133], v[202:205], v[94:97]
	v_mfma_f32_16x16x32_bf16 v[90:93], v[160:163], v[202:205], v[90:93]
	v_mfma_f32_16x16x32_bf16 v[78:81], v[130:133], v[210:213], v[78:81]
	v_mfma_f32_16x16x32_bf16 v[74:77], v[160:163], v[210:213], v[74:77]
	v_mfma_f32_16x16x32_bf16 v[126:129], v[156:159], v[190:193], v[126:129]
	v_mfma_f32_16x16x32_bf16 v[122:125], v[164:167], v[190:193], v[122:125]
	v_mfma_f32_16x16x32_bf16 v[110:113], v[156:159], v[198:201], v[110:113]
	v_mfma_f32_16x16x32_bf16 v[106:109], v[164:167], v[198:201], v[106:109]
	v_mfma_f32_16x16x32_bf16 v[94:97], v[156:159], v[206:209], v[94:97]
	v_mfma_f32_16x16x32_bf16 v[90:93], v[164:167], v[206:209], v[90:93]
	v_mfma_f32_16x16x32_bf16 v[78:81], v[156:159], v[214:217], v[78:81]
	v_mfma_f32_16x16x32_bf16 v[74:77], v[164:167], v[214:217], v[74:77]
	s_setprio 0
	s_barrier
	s_add_i32 s10, 0, 0x1c000
	s_add_i32 s11, s45, s71
	v_add_u32_e32 v138, s10, v141
	v_lshl_add_u64 v[172:173], v[172:173], 0, s[26:27]
	s_mov_b32 m0, s11
	ds_read_b128 v[218:221], v138
	ds_read_b128 v[222:225], v138 offset:1024
	ds_read_b128 v[226:229], v138 offset:2048
	ds_read_b128 v[230:233], v138 offset:3072
	global_load_lds_dwordx4 v[172:173], off
	v_lshl_add_u64 v[172:173], v[234:235], 0, s[26:27]
	s_add_i32 m0, s11, 0x2000
	s_nop 0
	global_load_lds_dwordx4 v[172:173], off
	s_barrier
	s_waitcnt lgkmcnt(0)
	s_setprio 1
	s_waitcnt lgkmcnt(0)
	v_mfma_f32_16x16x32_bf16 v[118:121], v[218:221], v[168:171], v[118:121]
	v_mfma_f32_16x16x32_bf16 v[114:117], v[226:229], v[168:171], v[114:117]
	v_mfma_f32_16x16x32_bf16 v[102:105], v[218:221], v[194:197], v[102:105]
	v_mfma_f32_16x16x32_bf16 v[98:101], v[226:229], v[194:197], v[98:101]
	v_mfma_f32_16x16x32_bf16 v[86:89], v[218:221], v[202:205], v[86:89]
	v_mfma_f32_16x16x32_bf16 v[82:85], v[226:229], v[202:205], v[82:85]
	v_mfma_f32_16x16x32_bf16 v[70:73], v[218:221], v[210:213], v[70:73]
	v_mfma_f32_16x16x32_bf16 v[66:69], v[226:229], v[210:213], v[66:69]
	v_mfma_f32_16x16x32_bf16 v[118:121], v[222:225], v[190:193], v[118:121]
	v_mfma_f32_16x16x32_bf16 v[114:117], v[230:233], v[190:193], v[114:117]
	v_mfma_f32_16x16x32_bf16 v[102:105], v[222:225], v[198:201], v[102:105]
	v_mfma_f32_16x16x32_bf16 v[98:101], v[230:233], v[198:201], v[98:101]
	v_mfma_f32_16x16x32_bf16 v[86:89], v[222:225], v[206:209], v[86:89]
	v_mfma_f32_16x16x32_bf16 v[82:85], v[230:233], v[206:209], v[82:85]
	v_mfma_f32_16x16x32_bf16 v[70:73], v[222:225], v[214:217], v[70:73]
	v_mfma_f32_16x16x32_bf16 v[66:69], v[230:233], v[214:217], v[66:69]
	s_setprio 0
	s_mov_b32 m0, s14
	v_lshl_add_u64 v[172:173], v[236:237], 0, s[26:27]
	s_barrier
	ds_read_b128 v[168:171], v183 offset:49152
	ds_read_b128 v[190:193], v183 offset:50176
	ds_read_b128 v[194:197], v183 offset:51200
	ds_read_b128 v[198:201], v183 offset:52224
	ds_read_b128 v[202:205], v183 offset:53248
	ds_read_b128 v[206:209], v183 offset:54272
	ds_read_b128 v[210:213], v183 offset:55296
	ds_read_b128 v[214:217], v183 offset:56320
	global_load_lds_dwordx4 v[172:173], off
	v_lshl_add_u64 v[172:173], v[238:239], 0, s[26:27]
	s_mov_b32 m0, s15
	s_nop 0
	global_load_lds_dwordx4 v[172:173], off
	s_barrier
	s_waitcnt lgkmcnt(0)
	s_setprio 1
	s_waitcnt lgkmcnt(0)
	v_mfma_f32_16x16x32_bf16 v[62:65], v[130:133], v[168:171], v[62:65]
	v_mfma_f32_16x16x32_bf16 v[58:61], v[160:163], v[168:171], v[58:61]
	v_mfma_f32_16x16x32_bf16 v[46:49], v[130:133], v[194:197], v[46:49]
	v_mfma_f32_16x16x32_bf16 v[42:45], v[160:163], v[194:197], v[42:45]
	v_mfma_f32_16x16x32_bf16 v[30:33], v[130:133], v[202:205], v[30:33]
	v_mfma_f32_16x16x32_bf16 v[26:29], v[160:163], v[202:205], v[26:29]
	v_mfma_f32_16x16x32_bf16 v[14:17], v[130:133], v[210:213], v[14:17]
	v_mfma_f32_16x16x32_bf16 v[10:13], v[160:163], v[210:213], v[10:13]
	v_mfma_f32_16x16x32_bf16 v[62:65], v[156:159], v[190:193], v[62:65]
	v_mfma_f32_16x16x32_bf16 v[58:61], v[164:167], v[190:193], v[58:61]
	v_mfma_f32_16x16x32_bf16 v[46:49], v[156:159], v[198:201], v[46:49]
	v_mfma_f32_16x16x32_bf16 v[42:45], v[164:167], v[198:201], v[42:45]
	v_mfma_f32_16x16x32_bf16 v[30:33], v[156:159], v[206:209], v[30:33]
	v_mfma_f32_16x16x32_bf16 v[26:29], v[164:167], v[206:209], v[26:29]
	v_mfma_f32_16x16x32_bf16 v[14:17], v[156:159], v[214:217], v[14:17]
	v_mfma_f32_16x16x32_bf16 v[10:13], v[164:167], v[214:217], v[10:13]
	s_setprio 0
	s_barrier
	s_add_u32 s8, s8, 0x80080
	s_addc_u32 s9, s9, 0
	s_add_i32 s10, s10, s71
	v_lshl_add_u64 v[130:131], s[8:9], 0, v[134:135]
	s_mov_b32 m0, s10
	s_nop 0
	global_load_lds_dwordx4 v[130:131], off
	v_lshl_add_u64 v[130:131], s[8:9], 0, v[136:137]
	s_add_i32 m0, s10, 0x2000
	s_nop 0
	global_load_lds_dwordx4 v[130:131], off
	s_waitcnt vmcnt(6)
	s_barrier
	s_setprio 1
	v_mfma_f32_16x16x32_bf16 v[54:57], v[218:221], v[168:171], v[54:57]
	v_mfma_f32_16x16x32_bf16 v[50:53], v[226:229], v[168:171], v[50:53]
	v_mfma_f32_16x16x32_bf16 v[38:41], v[218:221], v[194:197], v[38:41]
	v_mfma_f32_16x16x32_bf16 v[34:37], v[226:229], v[194:197], v[34:37]
	v_mfma_f32_16x16x32_bf16 v[22:25], v[218:221], v[202:205], v[22:25]
	v_mfma_f32_16x16x32_bf16 v[18:21], v[226:229], v[202:205], v[18:21]
	v_mfma_f32_16x16x32_bf16 v[6:9], v[218:221], v[210:213], v[6:9]
	v_mfma_f32_16x16x32_bf16 v[2:5], v[226:229], v[210:213], v[2:5]
	v_mfma_f32_16x16x32_bf16 v[54:57], v[222:225], v[190:193], v[54:57]
	v_mfma_f32_16x16x32_bf16 v[50:53], v[230:233], v[190:193], v[50:53]
	v_mfma_f32_16x16x32_bf16 v[38:41], v[222:225], v[198:201], v[38:41]
	v_mfma_f32_16x16x32_bf16 v[34:37], v[230:233], v[198:201], v[34:37]
	v_mfma_f32_16x16x32_bf16 v[22:25], v[222:225], v[206:209], v[22:25]
	v_mfma_f32_16x16x32_bf16 v[18:21], v[230:233], v[206:209], v[18:21]
	v_mfma_f32_16x16x32_bf16 v[6:9], v[222:225], v[214:217], v[6:9]
	v_mfma_f32_16x16x32_bf16 v[2:5], v[230:233], v[214:217], v[2:5]
	s_setprio 0
	s_add_i32 s39, s39, 2
	s_add_u32 s6, s6, 0x100
	s_addc_u32 s7, s7, 0
	s_add_u32 s16, s16, 0x100
	s_addc_u32 s38, s38, 0
	s_cmp_gt_u32 s39, 29
	s_barrier
	s_cbranch_scc0 .LBB0_342
	v_bfe_u32 v224, v185, 4, 1
	v_mov_b32_e32 v225, 0
	v_mul_u32_u24_e32 v224, 24, v224
	s_add_i32 s62, s2, -4
	s_and_b32 s63, s2, 1
	s_lshr_b32 s64, s62, 1
	s_cmp_eq_u32 s63, 0
	s_cselect_b64 s[12:13], -1, 0
	s_cmp_gt_i32 s62, 1
	s_cselect_b64 s[62:63], -1, 0
	s_and_b64 s[12:13], s[12:13], s[62:63]
	s_cmp_lt_u32 s64, 3
	s_cselect_b64 s[62:63], -1, 0
	s_lshl_b32 s64, s64, 6
	s_and_b64 s[12:13], s[12:13], s[62:63]
	s_mov_b32 s65, 0
	v_lshl_add_u64 v[196:197], s[64:65], 2, v[144:145]
	v_cndmask_b32_e64 v196, v146, v196, s[12:13]
	v_cndmask_b32_e64 v197, v147, v197, s[12:13]
	global_load_dwordx4 v[200:203], v[196:197], off
	global_load_dwordx4 v[204:207], v[196:197], off offset:64
	global_load_dwordx4 v[208:211], v[196:197], off offset:128
	global_load_dwordx4 v[212:215], v[196:197], off offset:192
	v_and_b32_e32 v131, 64, v185
	v_xor_b32_e32 v130, 16, v185
	v_add_u32_e32 v131, 64, v131
	v_cmp_lt_i32_e32 vcc, v130, v131
	s_cmp_gt_i32 s0, 63
	s_cselect_b64 s[6:7], -1, 0
	v_cndmask_b32_e32 v130, v185, v130, vcc
	v_lshlrev_b32_e32 v189, 2, v130
	v_xor_b32_e32 v130, 32, v185
	v_cmp_lt_i32_e32 vcc, v130, v131
	s_cmp_lt_i32 s0, 64
	s_cselect_b64 s[52:53], -1, 0
	v_cndmask_b32_e32 v130, v185, v130, vcc
	v_lshlrev_b32_e32 v190, 2, v130
	v_mul_f32_e32 v130, v127, v127
	v_fmac_f32_e32 v130, v126, v126
	v_fmac_f32_e32 v130, v128, v128
	v_fmac_f32_e32 v130, v129, v129
	v_fmac_f32_e32 v130, v122, v122
	v_fmac_f32_e32 v130, v123, v123
	v_fmac_f32_e32 v130, v124, v124
	v_fmac_f32_e32 v130, v125, v125
	v_fmac_f32_e32 v130, v118, v118
	v_fmac_f32_e32 v130, v119, v119
	v_fmac_f32_e32 v130, v120, v120
	v_fmac_f32_e32 v130, v121, v121
	v_fmac_f32_e32 v130, v114, v114
	v_fmac_f32_e32 v130, v115, v115
	v_fmac_f32_e32 v130, v116, v116
	v_fmac_f32_e32 v130, v117, v117
	s_cmp_gt_i32 s2, 3
	s_cselect_b64 s[10:11], -1, 0
	s_cmp_gt_u32 s2, 9
	s_cselect_b64 s[12:13], -1, 0
	v_mov_b32_e32 v131, v130
	s_nop 1
	v_permlane16_swap_b32_e32 v131, v130
	v_add_f32_e32 v130, v130, v131
	s_cmp_lg_u32 s2, 10
	s_cselect_b64 s[60:61], -1, 0
	s_add_i32 s1, s2, -4
	s_lshl_b32 s39, s2, 8
	s_lshr_b32 s8, s1, 1
	s_and_b32 s9, s2, 1
	s_cmp_eq_u32 s9, 0
	s_cselect_b64 s[2:3], -1, 0
	s_cmp_gt_u32 s1, 1
	s_cselect_b64 s[54:55], -1, 0
	s_lshl_b32 s1, s9, 8
	v_mov_b32_e32 v131, v130
	s_nop 1
	v_permlane32_swap_b32_e32 v131, v130
	v_add_f32_e32 v130, v130, v131
	s_and_b64 s[58:59], s[2:3], s[54:55]
	s_or_b32 s45, s1, s34
	s_lshl_b32 s16, s8, 6
	v_fmamk_f32 v130, v130, 0x3c800000, v188
	s_cmp_lg_u32 s8, 1
	v_rsq_f32_e32 v158, v130
	s_cselect_b64 s[56:57], -1, 0
	s_lshl_b32 s47, s0, 8
	v_readlane_b32 s0, v253, 42
	s_add_i32 s47, s47, s0
	v_add_u32_e32 v138, s39, v175
	v_or_b32_e32 v156, s47, v1
	s_ashr_i32 s38, s47, 11
	s_mov_b64 s[0:1], -1
	s_waitcnt vmcnt(0)
	s_and_b64 vcc, exec, s[10:11]
	s_cbranch_vccz .LBB0_429
	v_add_u32_e32 v164, 0xffffc000, v156
	v_and_b32_e32 v131, 0x7cf, v156
	v_ashrrev_i32_e32 v130, 3, v164
	v_cndmask_b32_e64 v165, v131, v174, s[6:7]
	v_mov_b32_e32 v131, s38
	v_cndmask_b32_e64 v162, v131, v130, s[6:7]
	s_and_b64 vcc, exec, s[12:13]
	s_cbranch_vccz .LBB0_359
	s_andn2_b64 vcc, exec, s[60:61]
	s_cbranch_vccnz .LBB0_355
	v_add_u32_e32 v132, 7, v165
	v_mov_b32_e32 v133, v139
	v_mad_i64_i32 v[132:133], s[0:1], v162, 15, v[132:133]
	v_ashrrev_i32_e32 v157, 31, v156
	v_readlane_b32 s0, v253, 43
	v_lshlrev_b64 v[130:131], 11, v[156:157]
	v_lshlrev_b64 v[132:133], 12, v[132:133]
	v_readlane_b32 s1, v253, 44
	v_lshl_add_u64 v[130:131], s[24:25], 0, v[130:131]
	v_lshl_add_u64 v[130:131], v[138:139], 1, v[130:131]
	v_lshl_add_u64 v[132:133], s[0:1], 0, v[132:133]
	v_cvt_pk_bf16_f32 v216, v126, v127
	v_cvt_pk_bf16_f32 v217, v128, v129
	s_and_b64 vcc, exec, s[6:7]
	v_lshl_add_u64 v[132:133], v[138:139], 2, v[132:133]
	s_cbranch_vccz .LBB0_348
	global_store_dwordx4 v[132:133], v[126:129], off

.LBB0_431:
	v_mul_f32_e32 v114, v111, v111
	v_fmac_f32_e32 v114, v110, v110
	v_fmac_f32_e32 v114, v112, v112
	v_fmac_f32_e32 v114, v113, v113
	v_fmac_f32_e32 v114, v106, v106
	v_fmac_f32_e32 v114, v107, v107
	v_fmac_f32_e32 v114, v108, v108
	v_fmac_f32_e32 v114, v109, v109
	v_fmac_f32_e32 v114, v102, v102
	v_fmac_f32_e32 v114, v103, v103
	v_fmac_f32_e32 v114, v104, v104
	v_fmac_f32_e32 v114, v105, v105
	v_fmac_f32_e32 v114, v98, v98
	v_fmac_f32_e32 v114, v99, v99
	v_fmac_f32_e32 v114, v100, v100
	v_fmac_f32_e32 v114, v101, v101
	v_or_b32_e32 v118, s47, v179
	s_mov_b64 s[8:9], -1
	s_andn2_b64 vcc, exec, s[10:11]
	v_mov_b32_e32 v115, v114
	s_nop 1
	v_permlane16_swap_b32_e32 v115, v114
	v_add_f32_e32 v114, v114, v115
	v_mov_b32_e32 v115, v114
	s_nop 1
	v_permlane32_swap_b32_e32 v115, v114
	v_add_f32_e32 v114, v114, v115
	v_fmamk_f32 v114, v114, 0x3c800000, v188
	v_rsq_f32_e32 v120, v114
	v_cndmask_b32_e64 v114, 0, 1, s[10:11]
	v_cmp_ne_u32_e64 s[2:3], 1, v114
	v_cndmask_b32_e64 v114, 0, 1, s[12:13]
	v_cmp_ne_u32_e64 s[0:1], 1, v114
	s_cbranch_vccnz .LBB0_517
	v_add_u32_e32 v126, 0xffffc000, v118
	v_and_b32_e32 v115, 0x7df, v118
	v_ashrrev_i32_e32 v114, 3, v126
	v_cndmask_b32_e64 v127, v115, v174, s[6:7]
	v_mov_b32_e32 v115, s38
	v_cndmask_b32_e64 v124, v115, v114, s[6:7]
	s_and_b64 vcc, exec, s[0:1]
	s_cbranch_vccnz .LBB0_447
	s_andn2_b64 vcc, exec, s[60:61]
	s_cbranch_vccnz .LBB0_443
	v_add_u32_e32 v116, 7, v127
	v_mov_b32_e32 v117, v139
	v_ashrrev_i32_e32 v119, 31, v118
	v_mad_i64_i32 v[116:117], s[8:9], v124, 15, v[116:117]
	v_readlane_b32 s10, v253, 43
	v_lshlrev_b64 v[114:115], 11, v[118:119]
	v_lshlrev_b64 v[116:117], 12, v[116:117]
	v_readlane_b32 s11, v253, 44
	v_lshl_add_u64 v[114:115], s[24:25], 0, v[114:115]
	v_cndmask_b32_e64 v119, 0, 1, s[6:7]
	v_lshl_add_u64 v[116:117], s[10:11], 0, v[116:117]
	v_lshl_add_u64 v[114:115], v[138:139], 1, v[114:115]
	v_cvt_pk_bf16_f32 v216, v110, v111
	v_cvt_pk_bf16_f32 v217, v112, v113
	v_cmp_ne_u32_e64 s[8:9], 1, v119
	s_andn2_b64 vcc, exec, s[6:7]
	v_lshl_add_u64 v[116:117], v[138:139], 2, v[116:117]
	s_cbranch_vccnz .LBB0_436
	global_store_dwordx4 v[116:117], v[110:113], off

.LBB0_519:
	v_mul_f32_e32 v98, v95, v95
	v_fmac_f32_e32 v98, v94, v94
	v_fmac_f32_e32 v98, v96, v96
	v_fmac_f32_e32 v98, v97, v97
	v_fmac_f32_e32 v98, v90, v90
	v_fmac_f32_e32 v98, v91, v91
	v_fmac_f32_e32 v98, v92, v92
	v_fmac_f32_e32 v98, v93, v93
	v_fmac_f32_e32 v98, v86, v86
	v_fmac_f32_e32 v98, v87, v87
	v_fmac_f32_e32 v98, v88, v88
	v_fmac_f32_e32 v98, v89, v89
	v_fmac_f32_e32 v98, v82, v82
	v_fmac_f32_e32 v98, v83, v83
	v_fmac_f32_e32 v98, v84, v84
	v_fmac_f32_e32 v98, v85, v85
	v_or_b32_e32 v104, s47, v180
	s_and_b64 vcc, exec, s[2:3]
	s_mov_b64 s[8:9], -1
	v_mov_b32_e32 v99, v98
	s_nop 1
	v_permlane16_swap_b32_e32 v99, v98
	v_add_f32_e32 v98, v98, v99
	v_mov_b32_e32 v99, v98
	s_nop 1
	v_permlane32_swap_b32_e32 v99, v98
	v_add_f32_e32 v98, v98, v99
	v_fmamk_f32 v98, v98, 0x3c800000, v188
	v_rsq_f32_e32 v102, v98
	s_cbranch_vccnz .LBB0_605
	v_add_u32_e32 v110, 0xffffc000, v104
	v_and_b32_e32 v99, 0x7ef, v104
	v_ashrrev_i32_e32 v98, 3, v110
	v_cndmask_b32_e64 v111, v99, v174, s[6:7]
	v_mov_b32_e32 v99, s38
	v_cndmask_b32_e64 v108, v99, v98, s[6:7]
	s_and_b64 vcc, exec, s[0:1]
	s_cbranch_vccnz .LBB0_535
	s_andn2_b64 vcc, exec, s[60:61]
	s_cbranch_vccnz .LBB0_531
	v_add_u32_e32 v100, 7, v111
	v_mov_b32_e32 v101, v139
	v_ashrrev_i32_e32 v105, 31, v104
	v_mad_i64_i32 v[100:101], s[8:9], v108, 15, v[100:101]
	v_readlane_b32 s10, v253, 43
	v_lshlrev_b64 v[98:99], 11, v[104:105]
	v_lshlrev_b64 v[100:101], 12, v[100:101]
	v_readlane_b32 s11, v253, 44
	v_lshl_add_u64 v[98:99], s[24:25], 0, v[98:99]
	v_cndmask_b32_e64 v103, 0, 1, s[6:7]
	v_lshl_add_u64 v[100:101], s[10:11], 0, v[100:101]
	v_lshl_add_u64 v[98:99], v[138:139], 1, v[98:99]
	v_cvt_pk_bf16_f32 v216, v94, v95
	v_cvt_pk_bf16_f32 v217, v96, v97
	v_cmp_ne_u32_e64 s[8:9], 1, v103
	s_andn2_b64 vcc, exec, s[6:7]
	v_lshl_add_u64 v[100:101], v[138:139], 2, v[100:101]
	s_cbranch_vccnz .LBB0_524
	global_store_dwordx4 v[100:101], v[94:97], off

.LBB0_607:
	v_mul_f32_e32 v82, v79, v79
	v_fmac_f32_e32 v82, v78, v78
	v_fmac_f32_e32 v82, v80, v80
	v_fmac_f32_e32 v82, v81, v81
	v_fmac_f32_e32 v82, v74, v74
	v_fmac_f32_e32 v82, v75, v75
	v_fmac_f32_e32 v82, v76, v76
	v_fmac_f32_e32 v82, v77, v77
	v_fmac_f32_e32 v82, v70, v70
	v_fmac_f32_e32 v82, v71, v71
	v_fmac_f32_e32 v82, v72, v72
	v_fmac_f32_e32 v82, v73, v73
	v_fmac_f32_e32 v82, v66, v66
	v_fmac_f32_e32 v82, v67, v67
	v_fmac_f32_e32 v82, v68, v68
	v_fmac_f32_e32 v82, v69, v69
	v_or_b32_e32 v88, s47, v181
	s_and_b64 vcc, exec, s[2:3]
	s_mov_b64 s[8:9], -1
	v_mov_b32_e32 v83, v82
	s_nop 1
	v_permlane16_swap_b32_e32 v83, v82
	v_add_f32_e32 v82, v82, v83
	v_mov_b32_e32 v83, v82
	s_nop 1
	v_permlane32_swap_b32_e32 v83, v82
	v_add_f32_e32 v82, v82, v83
	v_fmamk_f32 v82, v82, 0x3c800000, v188
	v_rsq_f32_e32 v86, v82
	s_cbranch_vccnz .LBB0_693
	v_add_u32_e32 v94, 0xffffc000, v88
	v_and_b32_e32 v83, 0x7ff, v88
	v_ashrrev_i32_e32 v82, 3, v94
	v_cndmask_b32_e64 v92, v83, v174, s[6:7]
	v_mov_b32_e32 v83, s38
	v_cndmask_b32_e64 v96, v83, v82, s[6:7]
	s_and_b64 vcc, exec, s[0:1]
	s_cbranch_vccnz .LBB0_623
	s_andn2_b64 vcc, exec, s[60:61]
	s_cbranch_vccnz .LBB0_619
	s_movk_i32 s8, 0x7f0
	v_mov_b32_e32 v93, v139
	v_ashrrev_i32_e32 v89, 31, v88
	v_cmp_lt_u32_e32 vcc, s8, v92
	v_mad_i64_i32 v[84:85], s[8:9], v96, 15, v[92:93]
	v_lshlrev_b64 v[82:83], 11, v[88:89]
	v_lshlrev_b64 v[90:91], 12, v[84:85]
	v_add_u32_e32 v84, 7, v92
	v_mov_b32_e32 v85, v139
	v_mad_i64_i32 v[84:85], s[8:9], v96, 15, v[84:85]
	v_lshl_add_u64 v[82:83], s[24:25], 0, v[82:83]
	v_lshlrev_b64 v[98:99], 12, v[84:85]
	v_lshl_add_u64 v[84:85], v[138:139], 1, v[82:83]
	v_cvt_pk_bf16_f32 v216, v78, v79
	v_cvt_pk_bf16_f32 v217, v80, v81
	s_or_b64 s[8:9], s[6:7], vcc
	v_cndmask_b32_e64 v83, v91, v99, s[6:7]
	v_cndmask_b32_e64 v82, v90, v98, s[6:7]
	s_and_saveexec_b64 s[10:11], s[8:9]
	s_cbranch_execz .LBB0_612
	s_and_b64 s[12:13], s[6:7], exec
	s_mov_b32 s12, 0x15478000
	s_cselect_b32 s12, s12, 0xc80f000
	s_add_u32 s12, s90, s12
	s_addc_u32 s13, s91, 0
	v_lshl_add_u64 v[90:91], s[12:13], 0, v[82:83]
	v_lshl_add_u64 v[90:91], v[138:139], 2, v[90:91]
	global_store_dwordx4 v[90:91], v[78:81], off

.LBB0_695:
	v_mul_f32_e32 v66, v63, v63
	v_fmac_f32_e32 v66, v62, v62
	v_fmac_f32_e32 v66, v64, v64
	v_fmac_f32_e32 v66, v65, v65
	v_fmac_f32_e32 v66, v58, v58
	v_fmac_f32_e32 v66, v59, v59
	v_fmac_f32_e32 v66, v60, v60
	v_fmac_f32_e32 v66, v61, v61
	v_fmac_f32_e32 v66, v54, v54
	v_fmac_f32_e32 v66, v55, v55
	v_fmac_f32_e32 v66, v56, v56
	v_fmac_f32_e32 v66, v57, v57
	v_fmac_f32_e32 v66, v50, v50
	v_fmac_f32_e32 v66, v51, v51
	v_fmac_f32_e32 v66, v52, v52
	v_fmac_f32_e32 v66, v53, v53
	s_addk_i32 s47, 0x80
	v_or_b32_e32 v70, s47, v1
	s_ashr_i32 s38, s47, 11
	s_and_b64 vcc, exec, s[2:3]
	v_mov_b32_e32 v67, v66
	s_nop 1
	v_permlane16_swap_b32_e32 v67, v66
	v_add_f32_e32 v66, v66, v67
	s_mov_b64 s[8:9], -1
	v_mov_b32_e32 v67, v66
	s_nop 1
	v_permlane32_swap_b32_e32 v67, v66
	v_add_f32_e32 v66, v66, v67
	v_fmamk_f32 v66, v66, 0x3c800000, v188
	v_rsq_f32_e32 v72, v66
	s_cbranch_vccnz .LBB0_781
	v_add_u32_e32 v78, 0xffffc000, v70
	v_and_b32_e32 v67, 0x7cf, v70
	v_ashrrev_i32_e32 v66, 3, v78
	v_cndmask_b32_e64 v79, v67, v174, s[6:7]
	v_mov_b32_e32 v67, s38
	v_cndmask_b32_e64 v76, v67, v66, s[6:7]
	s_and_b64 vcc, exec, s[0:1]
	s_cbranch_vccnz .LBB0_711
	s_andn2_b64 vcc, exec, s[60:61]
	s_cbranch_vccnz .LBB0_707
	v_add_u32_e32 v68, 7, v79
	v_mov_b32_e32 v69, v139
	v_ashrrev_i32_e32 v71, 31, v70
	v_mad_i64_i32 v[68:69], s[8:9], v76, 15, v[68:69]
	v_readlane_b32 s10, v253, 43
	v_lshlrev_b64 v[66:67], 11, v[70:71]
	v_lshlrev_b64 v[68:69], 12, v[68:69]
	v_readlane_b32 s11, v253, 44
	v_lshl_add_u64 v[66:67], s[24:25], 0, v[66:67]
	v_cndmask_b32_e64 v71, 0, 1, s[6:7]
	v_lshl_add_u64 v[68:69], s[10:11], 0, v[68:69]
	v_lshl_add_u64 v[66:67], v[138:139], 1, v[66:67]
	v_cvt_pk_bf16_f32 v216, v62, v63
	v_cvt_pk_bf16_f32 v217, v64, v65
	v_cmp_ne_u32_e64 s[8:9], 1, v71
	s_andn2_b64 vcc, exec, s[6:7]
	v_lshl_add_u64 v[68:69], v[138:139], 2, v[68:69]
	s_cbranch_vccnz .LBB0_700
	global_store_dwordx4 v[68:69], v[62:65], off

.LBB0_783:
	v_mul_f32_e32 v50, v47, v47
	v_fmac_f32_e32 v50, v46, v46
	v_fmac_f32_e32 v50, v48, v48
	v_fmac_f32_e32 v50, v49, v49
	v_fmac_f32_e32 v50, v42, v42
	v_fmac_f32_e32 v50, v43, v43
	v_fmac_f32_e32 v50, v44, v44
	v_fmac_f32_e32 v50, v45, v45
	v_fmac_f32_e32 v50, v38, v38
	v_fmac_f32_e32 v50, v39, v39
	v_fmac_f32_e32 v50, v40, v40
	v_fmac_f32_e32 v50, v41, v41
	v_fmac_f32_e32 v50, v34, v34
	v_fmac_f32_e32 v50, v35, v35
	v_fmac_f32_e32 v50, v36, v36
	v_fmac_f32_e32 v50, v37, v37
	v_or_b32_e32 v56, s47, v179
	s_and_b64 vcc, exec, s[2:3]
	s_mov_b64 s[8:9], -1
	v_mov_b32_e32 v51, v50
	s_nop 1
	v_permlane16_swap_b32_e32 v51, v50
	v_add_f32_e32 v50, v50, v51
	v_mov_b32_e32 v51, v50
	s_nop 1
	v_permlane32_swap_b32_e32 v51, v50
	v_add_f32_e32 v50, v50, v51
	v_fmamk_f32 v50, v50, 0x3c800000, v188
	v_rsq_f32_e32 v54, v50
	s_cbranch_vccnz .LBB0_869
	v_add_u32_e32 v62, 0xffffc000, v56
	v_and_b32_e32 v51, 0x7df, v56
	v_ashrrev_i32_e32 v50, 3, v62
	v_cndmask_b32_e64 v63, v51, v174, s[6:7]
	v_mov_b32_e32 v51, s38
	v_cndmask_b32_e64 v60, v51, v50, s[6:7]
	s_and_b64 vcc, exec, s[0:1]
	s_cbranch_vccnz .LBB0_799
	s_andn2_b64 vcc, exec, s[60:61]
	s_cbranch_vccnz .LBB0_795
	v_add_u32_e32 v52, 7, v63
	v_mov_b32_e32 v53, v139
	v_ashrrev_i32_e32 v57, 31, v56
	v_mad_i64_i32 v[52:53], s[8:9], v60, 15, v[52:53]
	v_readlane_b32 s10, v253, 43
	v_lshlrev_b64 v[50:51], 11, v[56:57]
	v_lshlrev_b64 v[52:53], 12, v[52:53]
	v_readlane_b32 s11, v253, 44
	v_lshl_add_u64 v[50:51], s[24:25], 0, v[50:51]
	v_cndmask_b32_e64 v55, 0, 1, s[6:7]
	v_lshl_add_u64 v[52:53], s[10:11], 0, v[52:53]
	v_lshl_add_u64 v[50:51], v[138:139], 1, v[50:51]
	v_cvt_pk_bf16_f32 v216, v46, v47
	v_cvt_pk_bf16_f32 v217, v48, v49
	v_cmp_ne_u32_e64 s[8:9], 1, v55
	s_andn2_b64 vcc, exec, s[6:7]
	v_lshl_add_u64 v[52:53], v[138:139], 2, v[52:53]
	s_cbranch_vccnz .LBB0_788
	global_store_dwordx4 v[52:53], v[46:49], off

.LBB0_871:
	v_mul_f32_e32 v34, v31, v31
	v_fmac_f32_e32 v34, v30, v30
	v_fmac_f32_e32 v34, v32, v32
	v_fmac_f32_e32 v34, v33, v33
	v_fmac_f32_e32 v34, v26, v26
	v_fmac_f32_e32 v34, v27, v27
	v_fmac_f32_e32 v34, v28, v28
	v_fmac_f32_e32 v34, v29, v29
	v_fmac_f32_e32 v34, v22, v22
	v_fmac_f32_e32 v34, v23, v23
	v_fmac_f32_e32 v34, v24, v24
	v_fmac_f32_e32 v34, v25, v25
	v_fmac_f32_e32 v34, v18, v18
	v_fmac_f32_e32 v34, v19, v19
	v_fmac_f32_e32 v34, v20, v20
	v_fmac_f32_e32 v34, v21, v21
	v_or_b32_e32 v40, s47, v180
	s_and_b64 vcc, exec, s[2:3]
	s_mov_b64 s[8:9], -1
	v_mov_b32_e32 v35, v34
	s_nop 1
	v_permlane16_swap_b32_e32 v35, v34
	v_add_f32_e32 v34, v34, v35
	v_mov_b32_e32 v35, v34
	s_nop 1
	v_permlane32_swap_b32_e32 v35, v34
	v_add_f32_e32 v34, v34, v35
	v_fmamk_f32 v34, v34, 0x3c800000, v188
	v_rsq_f32_e32 v38, v34
	s_cbranch_vccnz .LBB0_957
	v_add_u32_e32 v46, 0xffffc000, v40
	v_and_b32_e32 v35, 0x7ef, v40
	v_ashrrev_i32_e32 v34, 3, v46
	v_cndmask_b32_e64 v47, v35, v174, s[6:7]
	v_mov_b32_e32 v35, s38
	v_cndmask_b32_e64 v44, v35, v34, s[6:7]
	s_and_b64 vcc, exec, s[0:1]
	s_cbranch_vccnz .LBB0_887
	s_andn2_b64 vcc, exec, s[60:61]
	s_cbranch_vccnz .LBB0_883
	v_add_u32_e32 v36, 7, v47
	v_mov_b32_e32 v37, v139
	v_ashrrev_i32_e32 v41, 31, v40
	v_mad_i64_i32 v[36:37], s[8:9], v44, 15, v[36:37]
	v_readlane_b32 s10, v253, 43
	v_lshlrev_b64 v[34:35], 11, v[40:41]
	v_lshlrev_b64 v[36:37], 12, v[36:37]
	v_readlane_b32 s11, v253, 44
	v_lshl_add_u64 v[34:35], s[24:25], 0, v[34:35]
	v_cndmask_b32_e64 v39, 0, 1, s[6:7]
	v_lshl_add_u64 v[36:37], s[10:11], 0, v[36:37]
	v_lshl_add_u64 v[34:35], v[138:139], 1, v[34:35]
	v_cvt_pk_bf16_f32 v216, v30, v31
	v_cvt_pk_bf16_f32 v217, v32, v33
	v_cmp_ne_u32_e64 s[8:9], 1, v39
	s_andn2_b64 vcc, exec, s[6:7]
	v_lshl_add_u64 v[36:37], v[138:139], 2, v[36:37]
	s_cbranch_vccnz .LBB0_876
	global_store_dwordx4 v[36:37], v[30:33], off

.LBB0_959:
	v_mul_f32_e32 v18, v15, v15
	v_fmac_f32_e32 v18, v14, v14
	v_fmac_f32_e32 v18, v16, v16
	v_fmac_f32_e32 v18, v17, v17
	v_fmac_f32_e32 v18, v10, v10
	v_fmac_f32_e32 v18, v11, v11
	v_fmac_f32_e32 v18, v12, v12
	v_fmac_f32_e32 v18, v13, v13
	v_fmac_f32_e32 v18, v6, v6
	v_fmac_f32_e32 v18, v7, v7
	v_fmac_f32_e32 v18, v8, v8
	v_fmac_f32_e32 v18, v9, v9
	v_fmac_f32_e32 v18, v2, v2
	v_fmac_f32_e32 v18, v3, v3
	v_fmac_f32_e32 v18, v4, v4
	v_fmac_f32_e32 v18, v5, v5
	v_or_b32_e32 v22, s47, v181
	s_and_b64 vcc, exec, s[2:3]
	s_mov_b64 s[2:3], -1
	v_mov_b32_e32 v19, v18
	s_nop 1
	v_permlane16_swap_b32_e32 v19, v18
	v_add_f32_e32 v18, v18, v19
	v_mov_b32_e32 v19, v18
	s_nop 1
	v_permlane32_swap_b32_e32 v19, v18
	v_add_f32_e32 v18, v18, v19
	v_fmamk_f32 v18, v18, 0x3c800000, v188
	v_rsq_f32_e32 v24, v18
	s_cbranch_vccnz .LBB0_1045
	v_add_u32_e32 v30, 0xffffc000, v22
	v_and_b32_e32 v19, 0x7ff, v22
	v_ashrrev_i32_e32 v18, 3, v30
	v_cndmask_b32_e64 v28, v19, v174, s[6:7]
	v_mov_b32_e32 v19, s38
	v_cndmask_b32_e64 v32, v19, v18, s[6:7]
	s_and_b64 vcc, exec, s[0:1]
	s_mov_b64 s[0:1], -1
	s_cbranch_vccnz .LBB0_975
	s_andn2_b64 vcc, exec, s[60:61]
	s_cbranch_vccnz .LBB0_971
	s_movk_i32 s0, 0x7f0
	v_mov_b32_e32 v29, v139
	v_ashrrev_i32_e32 v23, 31, v22
	v_cmp_lt_u32_e32 vcc, s0, v28
	v_mad_i64_i32 v[20:21], s[0:1], v32, 15, v[28:29]
	v_lshlrev_b64 v[18:19], 11, v[22:23]
	v_lshlrev_b64 v[26:27], 12, v[20:21]
	v_add_u32_e32 v20, 7, v28
	v_mov_b32_e32 v21, v139
	v_mad_i64_i32 v[20:21], s[0:1], v32, 15, v[20:21]
	v_lshl_add_u64 v[18:19], s[24:25], 0, v[18:19]
	v_lshlrev_b64 v[34:35], 12, v[20:21]
	v_lshl_add_u64 v[20:21], v[138:139], 1, v[18:19]
	v_cvt_pk_bf16_f32 v216, v14, v15
	v_cvt_pk_bf16_f32 v217, v16, v17
	s_or_b64 s[0:1], s[6:7], vcc
	v_cndmask_b32_e64 v19, v27, v35, s[6:7]
	v_cndmask_b32_e64 v18, v26, v34, s[6:7]
	s_and_saveexec_b64 s[2:3], s[0:1]
	s_cbranch_execz .LBB0_964
	s_and_b64 s[8:9], s[6:7], exec
	s_mov_b32 s8, 0x15478000
	s_cselect_b32 s8, s8, 0xc80f000
	s_add_u32 s8, s90, s8
	s_addc_u32 s9, s91, 0
	v_lshl_add_u64 v[26:27], s[8:9], 0, v[18:19]
	v_lshl_add_u64 v[26:27], v[138:139], 2, v[26:27]
	global_store_dwordx4 v[26:27], v[14:17], off

.LBB0_1813:
	v_lshl_add_u64 v[88:89], v[54:55], 0, s[12:13]
	v_add_co_u32_e32 v112, vcc, 0x12305000, v88
	v_add_co_u32_e64 v114, s[0:1], s17, v88
	s_nop 0
	v_addc_co_u32_e32 v113, vcc, 0, v89, vcc
	global_load_dwordx4 v[96:99], v[112:113], off nt
	global_load_dwordx4 v[100:103], v[112:113], off offset:1024 nt
	global_load_dwordx4 v[104:107], v[112:113], off offset:2048 nt
	global_load_dwordx4 v[108:111], v[112:113], off offset:3072 nt
	v_addc_co_u32_e64 v115, s[0:1], 0, v89, s[0:1]
	s_add_u32 s12, s12, 0x1000
	s_addc_u32 s13, s13, 0
	s_cmpk_eq_u32 s12, 0x8000
	s_waitcnt vmcnt(3)
	v_and_b32_e32 v89, 0xffff0000, v96
	v_lshlrev_b32_e32 v88, 16, v96
	v_mul_f32_e32 v45, v89, v89
	v_lshlrev_b32_e32 v96, 16, v97
	v_fmac_f32_e32 v45, v88, v88
	v_and_b32_e32 v97, 0xffff0000, v97
	v_fmac_f32_e32 v45, v96, v96
	v_lshlrev_b32_e32 v112, 16, v98
	v_fmac_f32_e32 v45, v97, v97
	v_and_b32_e32 v113, 0xffff0000, v98
	v_fmac_f32_e32 v45, v112, v112
	v_lshlrev_b32_e32 v98, 16, v99
	v_fmac_f32_e32 v45, v113, v113
	v_and_b32_e32 v99, 0xffff0000, v99
	v_fmac_f32_e32 v45, v98, v98
	s_waitcnt vmcnt(2)
	v_lshlrev_b32_e32 v116, 16, v100
	v_fmac_f32_e32 v45, v99, v99
	v_and_b32_e32 v117, 0xffff0000, v100
	v_fmac_f32_e32 v45, v116, v116
	v_lshlrev_b32_e32 v100, 16, v101
	v_fmac_f32_e32 v45, v117, v117
	v_and_b32_e32 v101, 0xffff0000, v101
	v_fmac_f32_e32 v45, v100, v100
	v_lshlrev_b32_e32 v118, 16, v102
	v_fmac_f32_e32 v45, v101, v101
	v_and_b32_e32 v119, 0xffff0000, v102
	v_fmac_f32_e32 v45, v118, v118
	v_lshlrev_b32_e32 v102, 16, v103
	v_fmac_f32_e32 v45, v119, v119
	v_and_b32_e32 v103, 0xffff0000, v103
	v_fmac_f32_e32 v45, v102, v102
	s_waitcnt vmcnt(1)
	v_lshlrev_b32_e32 v120, 16, v104
	v_fmac_f32_e32 v45, v103, v103
	v_and_b32_e32 v121, 0xffff0000, v104
	v_fmac_f32_e32 v45, v120, v120
	v_lshlrev_b32_e32 v104, 16, v105
	v_fmac_f32_e32 v45, v121, v121
	v_and_b32_e32 v105, 0xffff0000, v105
	v_fmac_f32_e32 v45, v104, v104
	v_lshlrev_b32_e32 v122, 16, v106
	v_fmac_f32_e32 v45, v105, v105
	v_and_b32_e32 v123, 0xffff0000, v106
	v_fmac_f32_e32 v45, v122, v122
	v_lshlrev_b32_e32 v106, 16, v107
	v_fmac_f32_e32 v45, v123, v123
	v_and_b32_e32 v107, 0xffff0000, v107
	v_fmac_f32_e32 v45, v106, v106
	s_waitcnt vmcnt(0)
	v_lshlrev_b32_e32 v124, 16, v108
	v_fmac_f32_e32 v45, v107, v107
	v_and_b32_e32 v125, 0xffff0000, v108
	v_fmac_f32_e32 v45, v124, v124
	v_lshlrev_b32_e32 v108, 16, v109
	v_fmac_f32_e32 v45, v125, v125
	v_and_b32_e32 v109, 0xffff0000, v109
	v_fmac_f32_e32 v45, v108, v108
	v_lshlrev_b32_e32 v126, 16, v110
	v_fmac_f32_e32 v45, v109, v109
	v_and_b32_e32 v127, 0xffff0000, v110
	v_and_b32_e32 v110, 0xffff0000, v111
	v_lshlrev_b32_e32 v111, 16, v111
	v_fmac_f32_e32 v45, v126, v126
	v_pk_mul_f32 v[128:129], v[110:111], v[110:111]
	v_fmac_f32_e32 v45, v127, v127
	v_add_f32_e32 v45, v129, v45
	v_add_f32_e32 v45, v128, v45
	v_mov_b32_e32 v128, v45
	s_nop 1
	v_permlane32_swap_b32_e32 v128, v45
	v_add_f32_e32 v45, v45, v128
	v_mov_b32_e32 v128, v45
	s_nop 1
	v_permlane16_swap_b32_e32 v128, v45
	v_add_f32_e32 v45, v45, v128
	s_nop 1
	v_add_f32_dpp v45, v45, v45 row_ror:8 row_mask:0xf bank_mask:0xf
	s_nop 1
	v_add_f32_dpp v45, v45, v45 row_ror:4 row_mask:0xf bank_mask:0xf
	s_nop 1
	v_add_f32_dpp v45, v45, v45 row_ror:2 row_mask:0xf bank_mask:0xf
	s_nop 1
	v_add_f32_dpp v45, v45, v45 row_ror:1 row_mask:0xf bank_mask:0xf
	v_fmamk_f32 v45, v45, 0x3a000000, v35
	v_rsq_f32_e32 v128, v45
	s_nop 0
	v_pk_mul_f32 v[88:89], v[88:89], v[128:129] op_sel_hi:[1,0]
	v_pk_mul_f32 v[96:97], v[96:97], v[128:129] op_sel_hi:[1,0]
	v_pk_mul_f32 v[112:113], v[112:113], v[128:129] op_sel_hi:[1,0]
	v_pk_mul_f32 v[98:99], v[98:99], v[128:129] op_sel_hi:[1,0]
	v_pk_mul_f32 v[116:117], v[116:117], v[128:129] op_sel_hi:[1,0]
	v_pk_mul_f32 v[100:101], v[100:101], v[128:129] op_sel_hi:[1,0]
	v_pk_mul_f32 v[118:119], v[118:119], v[128:129] op_sel_hi:[1,0]
	v_pk_mul_f32 v[102:103], v[102:103], v[128:129] op_sel_hi:[1,0]
	v_pk_mul_f32 v[120:121], v[120:121], v[128:129] op_sel_hi:[1,0]
	v_pk_mul_f32 v[104:105], v[104:105], v[128:129] op_sel_hi:[1,0]
	v_pk_mul_f32 v[122:123], v[122:123], v[128:129] op_sel_hi:[1,0]
	v_pk_mul_f32 v[106:107], v[106:107], v[128:129] op_sel_hi:[1,0]
	v_pk_mul_f32 v[124:125], v[124:125], v[128:129] op_sel_hi:[1,0]
	v_pk_mul_f32 v[108:109], v[108:109], v[128:129] op_sel_hi:[1,0]
	v_pk_mul_f32 v[126:127], v[126:127], v[128:129] op_sel_hi:[1,0]
	v_pk_mul_f32 v[110:111], v[110:111], v[128:129] op_sel:[1,0] op_sel_hi:[0,0]
	v_pk_fma_f32 v[128:129], v[56:57], v[96:97], v[8:9]
	v_pk_fma_f32 v[88:89], v[58:59], v[88:89], v[6:7]
	v_pk_fma_f32 v[130:131], v[60:61], v[98:99], v[4:5]
	v_pk_fma_f32 v[98:99], v[62:63], v[112:113], v[2:3]
	v_pk_fma_f32 v[112:113], v[64:65], v[100:101], v[16:17]
	v_pk_fma_f32 v[100:101], v[66:67], v[116:117], v[14:15]
	v_pk_fma_f32 v[116:117], v[68:69], v[102:103], v[12:13]
	v_pk_fma_f32 v[102:103], v[70:71], v[118:119], v[10:11]
	v_pk_fma_f32 v[118:119], v[72:73], v[104:105], v[24:25]
	v_pk_fma_f32 v[104:105], v[74:75], v[120:121], v[22:23]
	v_pk_fma_f32 v[120:121], v[76:77], v[106:107], v[20:21]
	v_pk_fma_f32 v[106:107], v[78:79], v[122:123], v[18:19]
	v_pk_fma_f32 v[122:123], v[80:81], v[108:109], v[32:33]
	v_pk_fma_f32 v[108:109], v[82:83], v[124:125], v[30:31]
	v_pk_fma_f32 v[124:125], v[84:85], v[110:111], v[28:29]
	v_pk_fma_f32 v[110:111], v[86:87], v[126:127], v[26:27]
	v_cvt_pk_bf16_f32 v96, v88, v89
	v_cvt_pk_bf16_f32 v97, v128, v129
	v_cvt_pk_bf16_f32 v98, v98, v99
	v_cvt_pk_bf16_f32 v99, v130, v131
	v_cvt_pk_bf16_f32 v100, v100, v101
	v_cvt_pk_bf16_f32 v101, v112, v113
	v_cvt_pk_bf16_f32 v102, v102, v103
	v_cvt_pk_bf16_f32 v103, v116, v117
	v_cvt_pk_bf16_f32 v104, v104, v105
	v_cvt_pk_bf16_f32 v105, v118, v119
	v_cvt_pk_bf16_f32 v106, v106, v107
	v_cvt_pk_bf16_f32 v107, v120, v121
	v_cvt_pk_bf16_f32 v108, v108, v109
	v_cvt_pk_bf16_f32 v109, v122, v123
	v_cvt_pk_bf16_f32 v110, v110, v111
	v_cvt_pk_bf16_f32 v111, v124, v125
	global_store_dwordx4 v[114:115], v[96:99], off
	global_store_dwordx4 v[114:115], v[100:103], off offset:1024
	global_store_dwordx4 v[114:115], v[104:107], off offset:2048
	global_store_dwordx4 v[114:115], v[108:111], off offset:3072
	s_cbranch_scc0 .LBB0_1813
	v_add_u32_e32 v1, s14, v1
	v_cmp_lt_i32_e32 vcc, s18, v1
	s_or_b64 s[8:9], vcc, s[8:9]
	v_add_u32_e32 v44, s16, v44
	s_andn2_b64 exec, exec, s[8:9]
	s_cbranch_execnz .LBB0_1812

.LBB0_1978:
	v_add_u32_e32 v102, v107, v109
	v_lshlrev_b64 v[2:3], 12, v[102:103]
	v_lshl_add_u64 v[98:99], v[104:105], 0, v[2:3]
	global_load_dwordx4 v[188:191], v[98:99], off
	global_load_dwordx4 v[192:195], v[98:99], off offset:32
	global_load_dwordx4 v[196:199], v[98:99], off offset:64
	global_load_dwordx4 v[200:203], v[98:99], off offset:96
	global_load_dwordx4 v[204:207], v[98:99], off offset:128
	global_load_dwordx4 v[208:211], v[98:99], off offset:160
	global_load_dwordx4 v[212:215], v[98:99], off offset:192
	global_load_dwordx4 v[216:219], v[98:99], off offset:224
	s_waitcnt lgkmcnt(14)
	ds_read_b128 v[6:9], v110
	ds_read_b128 v[70:73], v110 offset:32
	s_waitcnt lgkmcnt(1)
	s_waitcnt vmcnt(7)
	v_mfma_f32_32x32x16_bf16 v[50:65], v[6:9], v[188:191], 0
	ds_read_b128 v[6:9], v110 offset:8704
	ds_read_b128 v[74:77], v110 offset:8736
	s_waitcnt lgkmcnt(1)
	v_mfma_f32_32x32x16_bf16 v[34:49], v[6:9], v[188:191], 0
	ds_read_b128 v[6:9], v110 offset:17408
	ds_read_b128 v[78:81], v110 offset:17440
	s_waitcnt lgkmcnt(1)
	v_mfma_f32_32x32x16_bf16 v[18:33], v[6:9], v[188:191], 0
	ds_read_b128 v[6:9], v110 offset:26112
	ds_read_b128 v[82:85], v110 offset:26144
	s_waitcnt vmcnt(6)
	v_mfma_f32_32x32x16_bf16 v[50:65], v[70:73], v[192:195], v[50:65]
	s_waitcnt lgkmcnt(1)
	v_mfma_f32_32x32x16_bf16 v[2:17], v[6:9], v[188:191], 0
	v_mfma_f32_32x32x16_bf16 v[34:49], v[74:77], v[192:195], v[34:49]
	v_mfma_f32_32x32x16_bf16 v[18:33], v[78:81], v[192:195], v[18:33]
	s_waitcnt lgkmcnt(0)
	v_mfma_f32_32x32x16_bf16 v[2:17], v[82:85], v[192:195], v[2:17]
	ds_read_b128 v[66:69], v110 offset:64
	ds_read_b128 v[74:77], v110 offset:96
	s_waitcnt lgkmcnt(1)
	s_waitcnt vmcnt(5)
	v_mfma_f32_32x32x16_bf16 v[50:65], v[66:69], v[196:199], v[50:65]
	ds_read_b128 v[66:69], v110 offset:8768
	ds_read_b128 v[90:93], v110 offset:8800
	s_waitcnt lgkmcnt(1)
	v_mfma_f32_32x32x16_bf16 v[34:49], v[66:69], v[196:199], v[34:49]
	ds_read_b128 v[66:69], v110 offset:17472
	ds_read_b128 v[94:97], v110 offset:17504
	s_waitcnt lgkmcnt(1)
	v_mfma_f32_32x32x16_bf16 v[18:33], v[66:69], v[196:199], v[18:33]
	ds_read_b128 v[66:69], v110 offset:26176
	ds_read_b128 v[86:89], v110 offset:26208
	s_waitcnt vmcnt(4)
	v_mfma_f32_32x32x16_bf16 v[50:65], v[74:77], v[200:203], v[50:65]
	s_waitcnt lgkmcnt(1)
	v_mfma_f32_32x32x16_bf16 v[2:17], v[66:69], v[196:199], v[2:17]
	ds_read_b128 v[66:69], v110 offset:128
	v_mfma_f32_32x32x16_bf16 v[34:49], v[90:93], v[200:203], v[34:49]
	ds_read_b128 v[90:93], v110 offset:160
	v_mfma_f32_32x32x16_bf16 v[18:33], v[94:97], v[200:203], v[18:33]
	s_waitcnt lgkmcnt(2)
	v_mfma_f32_32x32x16_bf16 v[2:17], v[86:89], v[200:203], v[2:17]
	s_waitcnt lgkmcnt(1)
	s_waitcnt vmcnt(3)
	v_mfma_f32_32x32x16_bf16 v[50:65], v[66:69], v[204:207], v[50:65]
	s_waitcnt lgkmcnt(0)
	s_waitcnt vmcnt(2)
	v_mfma_f32_32x32x16_bf16 v[50:65], v[90:93], v[208:211], v[50:65]
	ds_read_b128 v[90:93], v110 offset:192
	ds_read_b128 v[112:115], v110 offset:8832
	ds_read_b128 v[116:119], v110 offset:8864
	ds_read_b128 v[120:123], v110 offset:17536
	ds_read_b128 v[124:127], v110 offset:17568
	ds_read_b128 v[128:131], v110 offset:224
	s_waitcnt lgkmcnt(5)
	s_waitcnt vmcnt(1)
	v_mfma_f32_32x32x16_bf16 v[50:65], v[90:93], v[212:215], v[50:65]
	ds_read_b128 v[132:135], v110 offset:26240
	ds_read_b128 v[136:139], v110 offset:26272
	ds_read_b128 v[140:143], v110 offset:8896
	ds_read_b128 v[144:147], v110 offset:8928
	ds_read_b128 v[148:151], v110 offset:17600
	ds_read_b128 v[98:101], v110 offset:17632
	ds_read_b128 v[152:155], v110 offset:26304
	ds_read_b128 v[90:93], v110 offset:26336
	s_waitcnt lgkmcnt(12)
	v_mfma_f32_32x32x16_bf16 v[34:49], v[112:115], v[204:207], v[34:49]
	s_waitcnt lgkmcnt(11)
	v_mfma_f32_32x32x16_bf16 v[34:49], v[116:119], v[208:211], v[34:49]
	s_waitcnt lgkmcnt(5)
	v_mfma_f32_32x32x16_bf16 v[34:49], v[140:143], v[212:215], v[34:49]
	s_waitcnt vmcnt(0)
	v_mfma_f32_32x32x16_bf16 v[50:65], v[128:131], v[216:219], v[50:65]
	s_nop 11
	v_not_b32_e32 v102, v50
	v_or_b32_e32 v111, 0x80000000, v50
	v_cmp_gt_i32_e64 s[0:1], 0, v50
	v_mfma_f32_32x32x16_bf16 v[18:33], v[120:123], v[204:207], v[18:33]
	v_not_b32_e32 v128, v51
	v_or_b32_e32 v129, 0x80000000, v51
	v_cndmask_b32_e64 v50, v111, v102, s[0:1]
	v_cmp_gt_i32_e64 s[0:1], 0, v51
	v_not_b32_e32 v130, v52
	v_or_b32_e32 v131, 0x80000000, v52
	v_cndmask_b32_e64 v51, v129, v128, s[0:1]
	v_cmp_gt_i32_e64 s[0:1], 0, v52
	v_mfma_f32_32x32x16_bf16 v[2:17], v[132:135], v[204:207], v[2:17]
	v_not_b32_e32 v156, v53
	v_or_b32_e32 v157, 0x80000000, v53
	v_cndmask_b32_e64 v52, v131, v130, s[0:1]
	v_cmp_gt_i32_e64 s[0:1], 0, v53
	v_not_b32_e32 v158, v54
	v_or_b32_e32 v159, 0x80000000, v54
	v_cndmask_b32_e64 v53, v157, v156, s[0:1]
	v_cmp_gt_i32_e64 s[0:1], 0, v54
	v_not_b32_e32 v160, v55
	v_or_b32_e32 v161, 0x80000000, v55
	v_cndmask_b32_e64 v54, v159, v158, s[0:1]
	v_cmp_gt_i32_e64 s[0:1], 0, v55
	v_not_b32_e32 v162, v56
	v_or_b32_e32 v163, 0x80000000, v56
	v_cndmask_b32_e64 v55, v161, v160, s[0:1]
	v_cmp_gt_i32_e64 s[0:1], 0, v56
	v_not_b32_e32 v164, v57
	v_or_b32_e32 v165, 0x80000000, v57
	v_cndmask_b32_e64 v56, v163, v162, s[0:1]
	v_cmp_gt_i32_e64 s[0:1], 0, v57
	v_not_b32_e32 v166, v58
	v_or_b32_e32 v167, 0x80000000, v58
	v_cndmask_b32_e64 v57, v165, v164, s[0:1]
	v_cmp_gt_i32_e64 s[0:1], 0, v58
	s_waitcnt lgkmcnt(4)
	v_mfma_f32_32x32x16_bf16 v[34:49], v[144:147], v[216:219], v[34:49]
	v_not_b32_e32 v168, v59
	v_or_b32_e32 v169, 0x80000000, v59
	v_cndmask_b32_e64 v58, v167, v166, s[0:1]
	v_cmp_gt_i32_e64 s[0:1], 0, v59
	v_not_b32_e32 v170, v60
	v_or_b32_e32 v171, 0x80000000, v60
	v_cndmask_b32_e64 v59, v169, v168, s[0:1]
	v_mfma_f32_32x32x16_bf16 v[18:33], v[124:127], v[208:211], v[18:33]
	v_cmp_gt_i32_e64 s[0:1], 0, v60
	v_not_b32_e32 v172, v61
	v_or_b32_e32 v173, 0x80000000, v61
	v_cndmask_b32_e64 v60, v171, v170, s[0:1]
	v_cmp_gt_i32_e64 s[0:1], 0, v61
	v_not_b32_e32 v174, v62
	v_or_b32_e32 v175, 0x80000000, v62
	v_mfma_f32_32x32x16_bf16 v[2:17], v[136:139], v[208:211], v[2:17]
	v_cndmask_b32_e64 v61, v173, v172, s[0:1]
	v_cmp_gt_i32_e64 s[0:1], 0, v62
	v_not_b32_e32 v102, v63
	v_or_b32_e32 v111, 0x80000000, v63
	v_cndmask_b32_e64 v62, v175, v174, s[0:1]
	v_cmp_gt_i32_e64 s[0:1], 0, v63
	v_not_b32_e32 v94, v35
	s_waitcnt lgkmcnt(3)
	v_mfma_f32_32x32x16_bf16 v[18:33], v[148:151], v[212:215], v[18:33]
	v_cndmask_b32_e64 v63, v111, v102, s[0:1]
	v_not_b32_e32 v102, v64
	v_or_b32_e32 v111, 0x80000000, v64
	v_cmp_gt_i32_e64 s[0:1], 0, v64
	v_or_b32_e32 v95, 0x80000000, v35
	v_not_b32_e32 v78, v36
	v_cndmask_b32_e64 v64, v111, v102, s[0:1]
	v_not_b32_e32 v102, v65
	v_or_b32_e32 v111, 0x80000000, v65
	v_cmp_gt_i32_e64 s[0:1], 0, v65
	v_or_b32_e32 v79, 0x80000000, v36
	s_waitcnt lgkmcnt(1)
	v_mfma_f32_32x32x16_bf16 v[2:17], v[152:155], v[212:215], v[2:17]
	v_cndmask_b32_e64 v65, v111, v102, s[0:1]
	v_not_b32_e32 v102, v34
	v_or_b32_e32 v111, 0x80000000, v34
	v_cmp_gt_i32_e64 s[0:1], 0, v34
	v_not_b32_e32 v74, v40
	v_or_b32_e32 v75, 0x80000000, v40
	v_cndmask_b32_e64 v34, v111, v102, s[0:1]
	v_cmp_gt_i32_e64 s[0:1], 0, v35
	v_not_b32_e32 v70, v42
	v_or_b32_e32 v71, 0x80000000, v42
	v_cndmask_b32_e64 v35, v95, v94, s[0:1]
	v_cmp_gt_i32_e64 s[0:1], 0, v36
	v_mfma_f32_32x32x16_bf16 v[18:33], v[98:101], v[216:219], v[18:33]
	v_and_b32_e32 v51, 0xffffff80, v51
	v_cndmask_b32_e64 v36, v79, v78, s[0:1]
	v_not_b32_e32 v78, v37
	v_or_b32_e32 v79, 0x80000000, v37
	v_cmp_gt_i32_e64 s[0:1], 0, v37
	v_and_b32_e32 v52, 0xffffff80, v52
	v_and_b32_e32 v53, 0xffffff80, v53
	v_cndmask_b32_e64 v37, v79, v78, s[0:1]
	v_not_b32_e32 v78, v38
	v_or_b32_e32 v79, 0x80000000, v38
	v_cmp_gt_i32_e64 s[0:1], 0, v38
	s_waitcnt lgkmcnt(0)
	v_mfma_f32_32x32x16_bf16 v[2:17], v[90:93], v[216:219], v[2:17]
	v_not_b32_e32 v66, v44
	v_cndmask_b32_e64 v38, v79, v78, s[0:1]
	v_not_b32_e32 v78, v39
	v_or_b32_e32 v79, 0x80000000, v39
	v_cmp_gt_i32_e64 s[0:1], 0, v39
	v_or_b32_e32 v67, 0x80000000, v44
	v_and_b32_e32 v54, 0xffffff80, v54
	v_cndmask_b32_e64 v39, v79, v78, s[0:1]
	v_cmp_gt_i32_e64 s[0:1], 0, v40
	v_and_b32_e32 v55, 0xffffff80, v55
	v_and_b32_e32 v56, 0xffffff80, v56
	v_cndmask_b32_e64 v40, v75, v74, s[0:1]
	v_not_b32_e32 v74, v41
	v_or_b32_e32 v75, 0x80000000, v41
	v_cmp_gt_i32_e64 s[0:1], 0, v41
	v_and_b32_e32 v57, 0xffffff80, v57
	v_and_b32_e32 v58, 0xffffff80, v58
	v_cndmask_b32_e64 v41, v75, v74, s[0:1]
	v_cmp_gt_i32_e64 s[0:1], 0, v42
	v_and_b32_e32 v59, 0xffffff80, v59
	v_and_b32_e32 v60, 0xffffff80, v60
	v_cndmask_b32_e64 v42, v71, v70, s[0:1]
	v_not_b32_e32 v70, v43
	v_or_b32_e32 v71, 0x80000000, v43
	v_cmp_gt_i32_e64 s[0:1], 0, v43
	v_and_b32_e32 v61, 0xffffff80, v61
	v_and_b32_e32 v62, 0xffffff80, v62
	v_cndmask_b32_e64 v43, v71, v70, s[0:1]
	v_cmp_gt_i32_e64 s[0:1], 0, v44
	v_and_b32_e32 v63, 0xffffff80, v63
	v_and_b32_e32 v64, 0xffffff80, v64
	v_cndmask_b32_e64 v44, v67, v66, s[0:1]
	v_not_b32_e32 v66, v45
	v_or_b32_e32 v67, 0x80000000, v45
	v_cmp_gt_i32_e64 s[0:1], 0, v45
	v_and_b32_e32 v65, 0xffffff80, v65
	v_and_b32_e32 v34, 0xffffff80, v34
	v_cndmask_b32_e64 v45, v67, v66, s[0:1]
	v_not_b32_e32 v66, v46
	v_or_b32_e32 v67, 0x80000000, v46
	v_cmp_gt_i32_e64 s[0:1], 0, v46
	v_and_b32_e32 v35, 0xffffff80, v35
	v_and_b32_e32 v36, 0xffffff80, v36
	v_cndmask_b32_e64 v46, v67, v66, s[0:1]
	v_not_b32_e32 v66, v47
	v_or_b32_e32 v67, 0x80000000, v47
	v_cmp_gt_i32_e64 s[0:1], 0, v47
	v_and_b32_e32 v37, 0xffffff80, v37
	v_and_b32_e32 v38, 0xffffff80, v38
	v_cndmask_b32_e64 v47, v67, v66, s[0:1]
	v_not_b32_e32 v66, v48
	v_or_b32_e32 v67, 0x80000000, v48
	v_cmp_gt_i32_e64 s[0:1], 0, v48
	v_and_b32_e32 v39, 0xffffff80, v39
	v_and_b32_e32 v40, 0xffffff80, v40
	v_cndmask_b32_e64 v48, v67, v66, s[0:1]
	v_not_b32_e32 v66, v49
	v_or_b32_e32 v67, 0x80000000, v49
	v_cmp_gt_i32_e64 s[0:1], 0, v49
	v_and_b32_e32 v41, 0xffffff80, v41
	v_and_b32_e32 v42, 0xffffff80, v42
	v_cndmask_b32_e64 v49, v67, v66, s[0:1]
	v_not_b32_e32 v66, v18
	v_or_b32_e32 v67, 0x80000000, v18
	v_cmp_gt_i32_e64 s[0:1], 0, v18
	v_and_b32_e32 v43, 0xffffff80, v43
	v_and_b32_e32 v44, 0xffffff80, v44
	v_cndmask_b32_e64 v18, v67, v66, s[0:1]
	v_not_b32_e32 v66, v19
	v_or_b32_e32 v67, 0x80000000, v19
	v_cmp_gt_i32_e64 s[0:1], 0, v19
	v_and_b32_e32 v45, 0xffffff80, v45
	v_and_b32_e32 v46, 0xffffff80, v46
	v_cndmask_b32_e64 v19, v67, v66, s[0:1]
	v_not_b32_e32 v66, v20
	v_or_b32_e32 v67, 0x80000000, v20
	v_cmp_gt_i32_e64 s[0:1], 0, v20
	v_and_b32_e32 v47, 0xffffff80, v47
	v_and_b32_e32 v48, 0xffffff80, v48
	v_cndmask_b32_e64 v20, v67, v66, s[0:1]
	v_not_b32_e32 v66, v21
	v_or_b32_e32 v67, 0x80000000, v21
	v_cmp_gt_i32_e64 s[0:1], 0, v21
	v_and_b32_e32 v49, 0xffffff80, v49
	v_and_b32_e32 v50, 0xffffff80, v50
	v_cndmask_b32_e64 v21, v67, v66, s[0:1]
	v_not_b32_e32 v66, v22
	v_or_b32_e32 v67, 0x80000000, v22
	v_cmp_gt_i32_e64 s[0:1], 0, v22
	v_sub_u32_e32 v51, v51, v108
	v_sub_u32_e32 v52, v52, v108
	v_cndmask_b32_e64 v22, v67, v66, s[0:1]
	v_not_b32_e32 v66, v23
	v_or_b32_e32 v67, 0x80000000, v23
	v_cmp_gt_i32_e64 s[0:1], 0, v23
	v_sub_u32_e32 v53, v53, v108
	v_sub_u32_e32 v54, v54, v108
	v_cndmask_b32_e64 v23, v67, v66, s[0:1]
	v_not_b32_e32 v66, v24
	v_or_b32_e32 v67, 0x80000000, v24
	v_cmp_gt_i32_e64 s[0:1], 0, v24
	v_sub_u32_e32 v55, v55, v108
	v_sub_u32_e32 v56, v56, v108
	v_cndmask_b32_e64 v24, v67, v66, s[0:1]
	v_not_b32_e32 v66, v25
	v_or_b32_e32 v67, 0x80000000, v25
	v_cmp_gt_i32_e64 s[0:1], 0, v25
	v_sub_u32_e32 v57, v57, v108
	v_sub_u32_e32 v58, v58, v108
	v_cndmask_b32_e64 v25, v67, v66, s[0:1]
	v_not_b32_e32 v66, v26
	v_or_b32_e32 v67, 0x80000000, v26
	v_cmp_gt_i32_e64 s[0:1], 0, v26
	v_sub_u32_e32 v59, v59, v108
	v_sub_u32_e32 v60, v60, v108
	v_cndmask_b32_e64 v26, v67, v66, s[0:1]
	v_not_b32_e32 v66, v27
	v_or_b32_e32 v67, 0x80000000, v27
	v_cmp_gt_i32_e64 s[0:1], 0, v27
	v_sub_u32_e32 v61, v61, v108
	v_sub_u32_e32 v62, v62, v108
	v_cndmask_b32_e64 v27, v67, v66, s[0:1]
	v_not_b32_e32 v66, v28
	v_or_b32_e32 v67, 0x80000000, v28
	v_cmp_gt_i32_e64 s[0:1], 0, v28
	v_sub_u32_e32 v63, v63, v108
	v_sub_u32_e32 v64, v64, v108
	v_cndmask_b32_e64 v28, v67, v66, s[0:1]
	v_not_b32_e32 v66, v29
	v_or_b32_e32 v67, 0x80000000, v29
	v_cmp_gt_i32_e64 s[0:1], 0, v29
	v_sub_u32_e32 v65, v65, v108
	v_sub_u32_e32 v34, v34, v108
	v_cndmask_b32_e64 v29, v67, v66, s[0:1]
	v_not_b32_e32 v66, v30
	v_or_b32_e32 v67, 0x80000000, v30
	v_cmp_gt_i32_e64 s[0:1], 0, v30
	v_sub_u32_e32 v35, v35, v108
	v_sub_u32_e32 v36, v36, v108
	v_cndmask_b32_e64 v30, v67, v66, s[0:1]
	v_not_b32_e32 v66, v31
	v_or_b32_e32 v67, 0x80000000, v31
	v_cmp_gt_i32_e64 s[0:1], 0, v31
	v_sub_u32_e32 v37, v37, v108
	v_sub_u32_e32 v38, v38, v108
	v_cndmask_b32_e64 v31, v67, v66, s[0:1]
	v_not_b32_e32 v66, v32
	v_or_b32_e32 v67, 0x80000000, v32
	v_cmp_gt_i32_e64 s[0:1], 0, v32
	v_sub_u32_e32 v39, v39, v108
	v_sub_u32_e32 v40, v40, v108
	v_cndmask_b32_e64 v32, v67, v66, s[0:1]
	v_not_b32_e32 v66, v33
	v_or_b32_e32 v67, 0x80000000, v33
	v_cmp_gt_i32_e64 s[0:1], 0, v33
	v_sub_u32_e32 v41, v41, v108
	v_sub_u32_e32 v42, v42, v108
	v_cndmask_b32_e64 v33, v67, v66, s[0:1]
	v_not_b32_e32 v66, v2
	v_or_b32_e32 v67, 0x80000000, v2
	v_cmp_gt_i32_e64 s[0:1], 0, v2
	v_sub_u32_e32 v43, v43, v108
	v_sub_u32_e32 v44, v44, v108
	v_cndmask_b32_e64 v2, v67, v66, s[0:1]
	v_not_b32_e32 v66, v3
	v_or_b32_e32 v67, 0x80000000, v3
	v_cmp_gt_i32_e64 s[0:1], 0, v3
	v_sub_u32_e32 v45, v45, v108
	v_sub_u32_e32 v46, v46, v108
	v_cndmask_b32_e64 v3, v67, v66, s[0:1]
	v_not_b32_e32 v66, v4
	v_or_b32_e32 v67, 0x80000000, v4
	v_cmp_gt_i32_e64 s[0:1], 0, v4
	v_sub_u32_e32 v47, v47, v108
	v_sub_u32_e32 v48, v48, v108
	v_cndmask_b32_e64 v4, v67, v66, s[0:1]
	v_not_b32_e32 v66, v5
	v_or_b32_e32 v67, 0x80000000, v5
	v_cmp_gt_i32_e64 s[0:1], 0, v5
	v_sub_u32_e32 v49, v49, v108
	v_bitop3_b32 v50, v50, s17, v108 bitop3:0x36
	v_cndmask_b32_e64 v5, v67, v66, s[0:1]
	v_not_b32_e32 v66, v6
	v_or_b32_e32 v67, 0x80000000, v6
	v_cmp_gt_i32_e64 s[0:1], 0, v6
	v_add_u32_e32 v51, 0x7e, v51
	v_add_u32_e32 v52, 0x7d, v52
	v_cndmask_b32_e64 v6, v67, v66, s[0:1]
	v_not_b32_e32 v66, v7
	v_or_b32_e32 v67, 0x80000000, v7
	v_cmp_gt_i32_e64 s[0:1], 0, v7
	v_add_u32_e32 v53, 0x7c, v53
	v_add_u32_e32 v54, 0x77, v54
	v_cndmask_b32_e64 v7, v67, v66, s[0:1]
	v_not_b32_e32 v66, v8
	v_or_b32_e32 v67, 0x80000000, v8
	v_cmp_gt_i32_e64 s[0:1], 0, v8
	v_add_u32_e32 v55, 0x76, v55
	v_add_u32_e32 v56, 0x75, v56
	v_cndmask_b32_e64 v8, v67, v66, s[0:1]
	v_not_b32_e32 v66, v9
	v_or_b32_e32 v67, 0x80000000, v9
	v_cmp_gt_i32_e64 s[0:1], 0, v9
	v_add_u32_e32 v57, 0x74, v57
	v_add_u32_e32 v58, 0x6f, v58
	v_cndmask_b32_e64 v9, v67, v66, s[0:1]
	v_not_b32_e32 v66, v10
	v_or_b32_e32 v67, 0x80000000, v10
	v_cmp_gt_i32_e64 s[0:1], 0, v10
	v_add_u32_e32 v59, 0x6e, v59
	v_add_u32_e32 v60, 0x6d, v60
	v_cndmask_b32_e64 v10, v67, v66, s[0:1]
	v_not_b32_e32 v66, v11
	v_or_b32_e32 v67, 0x80000000, v11
	v_cmp_gt_i32_e64 s[0:1], 0, v11
	v_add_u32_e32 v61, 0x6c, v61
	v_add_u32_e32 v62, 0x67, v62
	v_cndmask_b32_e64 v11, v67, v66, s[0:1]
	v_not_b32_e32 v66, v12
	v_or_b32_e32 v67, 0x80000000, v12
	v_cmp_gt_i32_e64 s[0:1], 0, v12
	v_add_u32_e32 v63, 0x66, v63
	v_add_u32_e32 v64, 0x65, v64
	v_cndmask_b32_e64 v12, v67, v66, s[0:1]
	v_not_b32_e32 v66, v13
	v_or_b32_e32 v67, 0x80000000, v13
	v_cmp_gt_i32_e64 s[0:1], 0, v13
	v_add_u32_e32 v65, 0x64, v65
	v_add_u32_e32 v34, 0x5f, v34
	v_cndmask_b32_e64 v13, v67, v66, s[0:1]
	v_not_b32_e32 v66, v14
	v_or_b32_e32 v67, 0x80000000, v14
	v_cmp_gt_i32_e64 s[0:1], 0, v14
	v_add_u32_e32 v35, 0x5e, v35
	v_add_u32_e32 v36, 0x5d, v36
	v_cndmask_b32_e64 v14, v67, v66, s[0:1]
	v_not_b32_e32 v66, v15
	v_or_b32_e32 v67, 0x80000000, v15
	v_cmp_gt_i32_e64 s[0:1], 0, v15
	v_add_u32_e32 v37, 0x5c, v37
	v_add_u32_e32 v38, 0x57, v38
	v_cndmask_b32_e64 v15, v67, v66, s[0:1]
	v_not_b32_e32 v66, v16
	v_or_b32_e32 v67, 0x80000000, v16
	v_cmp_gt_i32_e64 s[0:1], 0, v16
	v_add_u32_e32 v39, 0x56, v39
	v_add_u32_e32 v40, 0x55, v40
	v_add_u32_e32 v41, 0x54, v41
	v_add_u32_e32 v42, 0x4f, v42
	v_add_u32_e32 v43, 0x4e, v43
	v_add_u32_e32 v44, 0x4d, v44
	v_add_u32_e32 v45, 0x4c, v45
	v_add_u32_e32 v46, 0x47, v46
	v_add_u32_e32 v47, 0x46, v47
	v_add_u32_e32 v48, 0x45, v48
	v_add_u32_e32 v49, 0x44, v49
	v_cndmask_b32_e64 v16, v67, v66, s[0:1]
	v_not_b32_e32 v66, v17
	v_or_b32_e32 v67, 0x80000000, v17
	v_cmp_gt_i32_e64 s[0:1], 0, v17
	v_max_u32_e32 v74, v34, v35
	v_min_u32_e32 v34, v34, v35
	v_cndmask_b32_e64 v17, v67, v66, s[0:1]
	v_max_u32_e32 v66, v50, v51
	v_min_u32_e32 v50, v50, v51
	v_max_u32_e32 v51, v53, v52
	v_min_u32_e32 v52, v53, v52
	v_max_u32_e32 v53, v54, v55
	v_min_u32_e32 v54, v54, v55
	v_max_u32_e32 v55, v57, v56
	v_min_u32_e32 v56, v57, v56
	v_max_u32_e32 v57, v58, v59
	v_min_u32_e32 v58, v58, v59
	v_max_u32_e32 v59, v61, v60
	v_min_u32_e32 v60, v61, v60
	v_max_u32_e32 v61, v62, v63
	v_min_u32_e32 v62, v62, v63
	v_max_u32_e32 v63, v65, v64
	v_min_u32_e32 v64, v65, v64
	v_max_u32_e32 v35, v37, v36
	v_min_u32_e32 v36, v37, v36
	v_max_u32_e32 v37, v38, v39
	v_min_u32_e32 v38, v38, v39
	v_max_u32_e32 v39, v41, v40
	v_min_u32_e32 v40, v41, v40
	v_max_u32_e32 v41, v42, v43
	v_min_u32_e32 v42, v42, v43
	v_max_u32_e32 v43, v45, v44
	v_min_u32_e32 v44, v45, v44
	v_max_u32_e32 v45, v46, v47
	v_min_u32_e32 v46, v46, v47
	v_max_u32_e32 v47, v49, v48
	v_min_u32_e32 v48, v49, v48
	v_max_u32_e32 v65, v66, v52
	v_min_u32_e32 v52, v66, v52
	v_max_u32_e32 v66, v50, v51
	v_min_u32_e32 v50, v50, v51
	v_max_u32_e32 v51, v56, v53
	v_min_u32_e32 v53, v56, v53
	v_max_u32_e32 v56, v55, v54
	v_min_u32_e32 v54, v55, v54
	v_max_u32_e32 v55, v57, v60
	v_min_u32_e32 v57, v57, v60
	v_max_u32_e32 v60, v58, v59
	v_min_u32_e32 v58, v58, v59
	v_max_u32_e32 v59, v64, v61
	v_min_u32_e32 v61, v64, v61
	v_max_u32_e32 v64, v63, v62
	v_min_u32_e32 v62, v63, v62
	v_max_u32_e32 v49, v74, v36
	v_min_u32_e32 v36, v74, v36
	v_max_u32_e32 v74, v34, v35
	v_min_u32_e32 v34, v34, v35
	v_max_u32_e32 v35, v40, v37
	v_min_u32_e32 v37, v40, v37
	v_max_u32_e32 v40, v39, v38
	v_min_u32_e32 v38, v39, v38
	v_max_u32_e32 v39, v41, v44
	v_min_u32_e32 v41, v41, v44
	v_max_u32_e32 v44, v42, v43
	v_min_u32_e32 v42, v42, v43
	v_max_u32_e32 v43, v48, v45
	v_min_u32_e32 v45, v48, v45
	v_max_u32_e32 v48, v47, v46
	v_min_u32_e32 v46, v47, v46
	v_max_u32_e32 v63, v65, v66
	v_min_u32_e32 v65, v65, v66
	v_max_u32_e32 v66, v52, v50
	v_min_u32_e32 v50, v52, v50
	v_max_u32_e32 v52, v54, v53
	v_min_u32_e32 v53, v54, v53
	v_max_u32_e32 v54, v56, v51
	v_min_u32_e32 v51, v56, v51
	v_max_u32_e32 v56, v55, v60
	v_min_u32_e32 v55, v55, v60
	v_max_u32_e32 v60, v57, v58
	v_min_u32_e32 v57, v57, v58
	v_max_u32_e32 v58, v62, v61
	v_min_u32_e32 v61, v62, v61
	v_max_u32_e32 v62, v64, v59
	v_min_u32_e32 v59, v64, v59
	v_max_u32_e32 v47, v49, v74
	v_min_u32_e32 v49, v49, v74
	v_max_u32_e32 v74, v36, v34
	v_min_u32_e32 v34, v36, v34
	v_max_u32_e32 v36, v38, v37
	v_min_u32_e32 v37, v38, v37
	v_max_u32_e32 v38, v40, v35
	v_min_u32_e32 v35, v40, v35
	v_max_u32_e32 v40, v39, v44
	v_min_u32_e32 v39, v39, v44
	v_max_u32_e32 v44, v41, v42
	v_min_u32_e32 v41, v41, v42
	v_max_u32_e32 v42, v46, v45
	v_min_u32_e32 v45, v46, v45
	v_max_u32_e32 v46, v48, v43
	v_min_u32_e32 v43, v48, v43
	v_max_u32_e32 v64, v63, v53
	v_min_u32_e32 v53, v63, v53
	v_max_u32_e32 v63, v65, v52
	v_min_u32_e32 v52, v65, v52
	v_max_u32_e32 v65, v66, v51
	v_min_u32_e32 v51, v66, v51
	v_max_u32_e32 v66, v50, v54
	v_min_u32_e32 v50, v50, v54
	v_max_u32_e32 v54, v61, v56
	v_min_u32_e32 v56, v61, v56
	v_max_u32_e32 v61, v58, v55
	v_min_u32_e32 v55, v58, v55
	v_max_u32_e32 v58, v59, v60
	v_min_u32_e32 v59, v59, v60
	v_max_u32_e32 v60, v62, v57
	v_min_u32_e32 v57, v62, v57
	v_max_u32_e32 v48, v47, v37
	v_min_u32_e32 v37, v47, v37
	v_max_u32_e32 v47, v49, v36
	v_min_u32_e32 v36, v49, v36
	v_max_u32_e32 v49, v74, v35
	v_min_u32_e32 v35, v74, v35
	v_max_u32_e32 v74, v34, v38
	v_min_u32_e32 v34, v34, v38
	v_max_u32_e32 v38, v45, v40
	v_min_u32_e32 v40, v45, v40
	v_max_u32_e32 v45, v42, v39
	v_min_u32_e32 v39, v42, v39
	v_max_u32_e32 v42, v43, v44
	v_min_u32_e32 v43, v43, v44
	v_max_u32_e32 v44, v46, v41
	v_min_u32_e32 v41, v46, v41
	v_max_u32_e32 v62, v64, v65
	v_min_u32_e32 v64, v64, v65
	v_max_u32_e32 v65, v63, v66
	v_min_u32_e32 v63, v63, v66
	v_max_u32_e32 v66, v53, v51
	v_min_u32_e32 v51, v53, v51
	v_max_u32_e32 v53, v52, v50
	v_min_u32_e32 v50, v52, v50
	v_max_u32_e32 v52, v59, v56
	v_min_u32_e32 v56, v59, v56
	v_max_u32_e32 v59, v57, v55
	v_min_u32_e32 v55, v57, v55
	v_max_u32_e32 v57, v58, v54
	v_min_u32_e32 v54, v58, v54
	v_max_u32_e32 v58, v60, v61
	v_min_u32_e32 v60, v60, v61
	v_max_u32_e32 v46, v48, v49
	v_min_u32_e32 v48, v48, v49
	v_max_u32_e32 v49, v47, v74
	v_min_u32_e32 v47, v47, v74
	v_max_u32_e32 v74, v37, v35
	v_min_u32_e32 v35, v37, v35
	v_max_u32_e32 v37, v36, v34
	v_min_u32_e32 v34, v36, v34
	v_max_u32_e32 v36, v43, v40
	v_min_u32_e32 v40, v43, v40
	v_max_u32_e32 v43, v41, v39
	v_min_u32_e32 v39, v41, v39
	v_max_u32_e32 v41, v42, v38
	v_min_u32_e32 v38, v42, v38
	v_max_u32_e32 v42, v44, v45
	v_min_u32_e32 v44, v44, v45
	v_max_u32_e32 v61, v62, v65
	v_min_u32_e32 v62, v62, v65
	v_max_u32_e32 v65, v64, v63
	v_min_u32_e32 v63, v64, v63
	v_max_u32_e32 v64, v66, v53
	v_min_u32_e32 v53, v66, v53
	v_max_u32_e32 v66, v51, v50
	v_min_u32_e32 v50, v51, v50
	v_max_u32_e32 v51, v55, v56
	v_min_u32_e32 v55, v55, v56
	v_max_u32_e32 v56, v59, v52
	v_min_u32_e32 v52, v59, v52
	v_max_u32_e32 v59, v60, v54
	v_min_u32_e32 v54, v60, v54
	v_max_u32_e32 v60, v58, v57
	v_min_u32_e32 v57, v58, v57
	v_max_u32_e32 v45, v46, v49
	v_min_u32_e32 v46, v46, v49
	v_max_u32_e32 v49, v48, v47
	v_min_u32_e32 v47, v48, v47
	v_max_u32_e32 v48, v74, v37
	v_min_u32_e32 v37, v74, v37
	v_max_u32_e32 v74, v35, v34
	v_min_u32_e32 v34, v35, v34
	v_max_u32_e32 v35, v39, v40
	v_min_u32_e32 v39, v39, v40
	v_max_u32_e32 v40, v43, v36
	v_min_u32_e32 v36, v43, v36
	v_max_u32_e32 v43, v44, v38
	v_min_u32_e32 v38, v44, v38
	v_max_u32_e32 v44, v42, v41
	v_min_u32_e32 v41, v42, v41
	v_max_u32_e32 v58, v61, v55
	v_min_u32_e32 v55, v61, v55
	v_max_u32_e32 v61, v62, v51
	v_min_u32_e32 v51, v62, v51
	v_max_u32_e32 v62, v65, v52
	v_min_u32_e32 v52, v65, v52
	v_max_u32_e32 v65, v63, v56
	v_min_u32_e32 v56, v63, v56
	v_max_u32_e32 v63, v64, v54
	v_min_u32_e32 v54, v64, v54
	v_max_u32_e32 v64, v53, v59
	v_min_u32_e32 v53, v53, v59
	v_max_u32_e32 v59, v66, v57
	v_min_u32_e32 v57, v66, v57
	v_max_u32_e32 v66, v50, v60
	v_max_u32_e32 v42, v45, v39
	v_min_u32_e32 v39, v45, v39
	v_max_u32_e32 v45, v46, v35
	v_min_u32_e32 v35, v46, v35
	v_max_u32_e32 v46, v49, v36
	v_min_u32_e32 v36, v49, v36
	v_max_u32_e32 v49, v47, v40
	v_min_u32_e32 v40, v47, v40
	v_max_u32_e32 v47, v48, v38
	v_min_u32_e32 v38, v48, v38
	v_max_u32_e32 v48, v37, v43
	v_min_u32_e32 v37, v37, v43
	v_max_u32_e32 v43, v74, v41
	v_min_u32_e32 v41, v74, v41
	v_max_u32_e32 v74, v34, v44
	v_min_u32_e32 v34, v34, v44
	v_and_b32_e32 v19, 0xffffff80, v19
	v_and_b32_e32 v20, 0xffffff80, v20
	v_and_b32_e32 v21, 0xffffff80, v21
	v_and_b32_e32 v22, 0xffffff80, v22
	v_and_b32_e32 v23, 0xffffff80, v23
	v_and_b32_e32 v24, 0xffffff80, v24
	v_and_b32_e32 v25, 0xffffff80, v25
	v_and_b32_e32 v26, 0xffffff80, v26
	v_and_b32_e32 v27, 0xffffff80, v27
	v_and_b32_e32 v28, 0xffffff80, v28
	v_and_b32_e32 v29, 0xffffff80, v29
	v_and_b32_e32 v30, 0xffffff80, v30
	v_and_b32_e32 v31, 0xffffff80, v31
	v_and_b32_e32 v32, 0xffffff80, v32
	v_and_b32_e32 v33, 0xffffff80, v33
	v_and_b32_e32 v3, 0xffffff80, v3
	v_and_b32_e32 v4, 0xffffff80, v4
	v_and_b32_e32 v5, 0xffffff80, v5
	v_and_b32_e32 v6, 0xffffff80, v6
	v_and_b32_e32 v7, 0xffffff80, v7
	v_and_b32_e32 v8, 0xffffff80, v8
	v_and_b32_e32 v9, 0xffffff80, v9
	v_and_b32_e32 v11, 0xffffff80, v11
	v_and_b32_e32 v12, 0xffffff80, v12
	v_and_b32_e32 v13, 0xffffff80, v13
	v_and_b32_e32 v15, 0xffffff80, v15
	v_and_b32_e32 v16, 0xffffff80, v16
	v_and_b32_e32 v17, 0xffffff80, v17
	v_min_u32_e32 v50, v50, v60
	v_max_u32_e32 v60, v58, v63
	v_min_u32_e32 v58, v58, v63
	v_max_u32_e32 v63, v61, v64
	v_min_u32_e32 v61, v61, v64
	v_max_u32_e32 v64, v62, v59
	v_min_u32_e32 v59, v62, v59
	v_max_u32_e32 v62, v65, v66
	v_min_u32_e32 v65, v65, v66
	v_max_u32_e32 v44, v42, v47
	v_min_u32_e32 v42, v42, v47
	v_max_u32_e32 v47, v45, v48
	v_min_u32_e32 v45, v45, v48
	v_max_u32_e32 v48, v46, v43
	v_min_u32_e32 v43, v46, v43
	v_max_u32_e32 v46, v49, v74
	v_min_u32_e32 v49, v49, v74
	v_max_u32_e32 v74, v39, v38
	v_min_u32_e32 v38, v39, v38
	v_max_u32_e32 v39, v35, v37
	v_min_u32_e32 v35, v35, v37
	v_max_u32_e32 v37, v36, v41
	v_min_u32_e32 v36, v36, v41
	v_max_u32_e32 v41, v40, v34
	v_and_b32_e32 v18, 0xffffff80, v18
	v_sub_u32_e32 v19, v19, v108
	v_sub_u32_e32 v20, v20, v108
	v_sub_u32_e32 v21, v21, v108
	v_sub_u32_e32 v22, v22, v108
	v_sub_u32_e32 v23, v23, v108
	v_sub_u32_e32 v24, v24, v108
	v_sub_u32_e32 v25, v25, v108
	v_sub_u32_e32 v26, v26, v108
	v_sub_u32_e32 v27, v27, v108
	v_sub_u32_e32 v28, v28, v108
	v_sub_u32_e32 v29, v29, v108
	v_sub_u32_e32 v30, v30, v108
	v_sub_u32_e32 v31, v31, v108
	v_sub_u32_e32 v32, v32, v108
	v_sub_u32_e32 v33, v33, v108
	v_and_b32_e32 v2, 0xffffff80, v2
	v_sub_u32_e32 v3, v3, v108
	v_sub_u32_e32 v4, v4, v108
	v_sub_u32_e32 v5, v5, v108
	v_sub_u32_e32 v6, v6, v108
	v_sub_u32_e32 v7, v7, v108
	v_sub_u32_e32 v8, v8, v108
	v_sub_u32_e32 v9, v9, v108
	v_and_b32_e32 v10, 0xffffff80, v10
	v_sub_u32_e32 v11, v11, v108
	v_sub_u32_e32 v12, v12, v108
	v_sub_u32_e32 v13, v13, v108
	v_and_b32_e32 v14, 0xffffff80, v14
	v_sub_u32_e32 v15, v15, v108
	v_sub_u32_e32 v16, v16, v108
	v_sub_u32_e32 v17, v17, v108
	v_max_u32_e32 v66, v55, v54
	v_min_u32_e32 v54, v55, v54
	v_max_u32_e32 v55, v51, v53
	v_min_u32_e32 v51, v51, v53
	v_max_u32_e32 v53, v52, v57
	v_min_u32_e32 v52, v52, v57
	v_max_u32_e32 v57, v56, v50
	v_min_u32_e32 v50, v56, v50
	v_max_u32_e32 v56, v60, v64
	v_min_u32_e32 v60, v60, v64
	v_max_u32_e32 v64, v63, v62
	v_min_u32_e32 v62, v63, v62
	v_max_u32_e32 v63, v58, v59
	v_min_u32_e32 v58, v58, v59
	v_max_u32_e32 v59, v61, v65
	v_min_u32_e32 v34, v40, v34
	v_max_u32_e32 v40, v44, v48
	v_min_u32_e32 v44, v44, v48
	v_max_u32_e32 v48, v47, v46
	v_min_u32_e32 v46, v47, v46
	v_max_u32_e32 v47, v42, v43
	v_min_u32_e32 v42, v42, v43
	v_max_u32_e32 v43, v45, v49
	v_min_u32_e32 v45, v45, v49
	v_max_u32_e32 v49, v74, v37
	v_min_u32_e32 v37, v74, v37
	v_max_u32_e32 v74, v39, v41
	v_bitop3_b32 v18, v18, 63, v108 bitop3:0x36
	v_add_u32_e32 v19, 62, v19
	v_add_u32_e32 v20, 61, v20
	v_add_u32_e32 v21, 60, v21
	v_add_u32_e32 v22, 55, v22
	v_add_u32_e32 v23, 54, v23
	v_add_u32_e32 v24, 53, v24
	v_add_u32_e32 v25, 52, v25
	v_add_u32_e32 v26, 47, v26
	v_add_u32_e32 v27, 46, v27
	v_add_u32_e32 v28, 45, v28
	v_add_u32_e32 v29, 44, v29
	v_add_u32_e32 v30, 39, v30
	v_add_u32_e32 v31, 38, v31
	v_add_u32_e32 v32, 37, v32
	v_add_u32_e32 v33, 36, v33
	v_bitop3_b32 v2, v2, 31, v108 bitop3:0x36
	v_add_u32_e32 v3, 30, v3
	v_add_u32_e32 v4, 29, v4
	v_add_u32_e32 v5, 28, v5
	v_add_u32_e32 v6, 23, v6
	v_add_u32_e32 v7, 22, v7
	v_add_u32_e32 v8, 21, v8
	v_add_u32_e32 v9, 20, v9
	v_bitop3_b32 v10, v10, 15, v108 bitop3:0x36
	v_add_u32_e32 v11, 14, v11
	v_add_u32_e32 v12, 13, v12
	v_add_u32_e32 v13, 12, v13
	v_bitop3_b32 v14, v14, 7, v108 bitop3:0x36
	v_add_u32_e32 v15, 6, v15
	v_add_u32_e32 v16, 5, v16
	v_add_u32_e32 v17, 4, v17
	v_min_u32_e32 v61, v61, v65
	v_max_u32_e32 v65, v66, v53
	v_min_u32_e32 v53, v66, v53
	v_max_u32_e32 v66, v55, v57
	v_min_u32_e32 v55, v55, v57
	v_max_u32_e32 v57, v54, v52
	v_min_u32_e32 v52, v54, v52
	v_max_u32_e32 v54, v51, v50
	v_min_u32_e32 v50, v51, v50
	v_min_u32_e32 v51, v56, v64
	v_min_u32_e32 v68, v63, v59
	v_min_u32_e32 v39, v39, v41
	v_max_u32_e32 v41, v38, v36
	v_min_u32_e32 v36, v38, v36
	v_max_u32_e32 v38, v35, v34
	v_min_u32_e32 v34, v35, v34
	v_min_u32_e32 v77, v42, v45
	v_min_u32_e32 v78, v49, v74
	v_min_u32_e32 v69, v58, v61
	v_min_u32_e32 v70, v65, v66
	v_min_u32_e32 v79, v37, v39
	v_min_u32_e32 v81, v36, v34
	v_max3_u32 v34, v51, v36, v34
	v_max3_u32 v37, v68, v37, v39
	v_max3_u32 v39, v58, v61, v78
	v_max3_u32 v51, v65, v66, v77
	v_max_u32_e32 v58, v18, v19
	v_min_u32_e32 v18, v18, v19
	v_max_u32_e32 v19, v21, v20
	v_min_u32_e32 v20, v21, v20
	v_max_u32_e32 v21, v22, v23
	v_min_u32_e32 v22, v22, v23
	v_max_u32_e32 v23, v25, v24
	v_min_u32_e32 v24, v25, v24
	v_max_u32_e32 v25, v26, v27
	v_min_u32_e32 v26, v26, v27
	v_max_u32_e32 v27, v29, v28
	v_min_u32_e32 v28, v29, v28
	v_max_u32_e32 v29, v30, v31
	v_min_u32_e32 v30, v30, v31
	v_max_u32_e32 v31, v33, v32
	v_min_u32_e32 v32, v33, v32
	v_max_u32_e32 v66, v2, v3
	v_min_u32_e32 v2, v2, v3
	v_max_u32_e32 v3, v5, v4
	v_min_u32_e32 v4, v5, v4
	v_max_u32_e32 v5, v6, v7
	v_min_u32_e32 v6, v6, v7
	v_max_u32_e32 v7, v9, v8
	v_min_u32_e32 v8, v9, v8
	v_max_u32_e32 v9, v10, v11
	v_min_u32_e32 v10, v10, v11
	v_max_u32_e32 v11, v13, v12
	v_min_u32_e32 v12, v13, v12
	v_max_u32_e32 v13, v14, v15
	v_min_u32_e32 v14, v14, v15
	v_max_u32_e32 v15, v17, v16
	v_min_u32_e32 v16, v17, v16
	v_max_u32_e32 v33, v58, v20
	v_min_u32_e32 v20, v58, v20
	v_max_u32_e32 v58, v18, v19
	v_min_u32_e32 v18, v18, v19
	v_max_u32_e32 v19, v24, v21
	v_min_u32_e32 v21, v24, v21
	v_max_u32_e32 v24, v23, v22
	v_min_u32_e32 v22, v23, v22
	v_max_u32_e32 v23, v25, v28
	v_min_u32_e32 v25, v25, v28
	v_max_u32_e32 v28, v26, v27
	v_min_u32_e32 v26, v26, v27
	v_max_u32_e32 v27, v32, v29
	v_min_u32_e32 v29, v32, v29
	v_max_u32_e32 v32, v31, v30
	v_min_u32_e32 v30, v31, v30
	v_max_u32_e32 v17, v66, v4
	v_min_u32_e32 v4, v66, v4
	v_max_u32_e32 v66, v2, v3
	v_min_u32_e32 v2, v2, v3
	v_max_u32_e32 v3, v8, v5
	v_min_u32_e32 v5, v8, v5
	v_max_u32_e32 v8, v7, v6
	v_min_u32_e32 v6, v7, v6
	v_max_u32_e32 v7, v9, v12
	v_min_u32_e32 v9, v9, v12
	v_max_u32_e32 v12, v10, v11
	v_min_u32_e32 v10, v10, v11
	v_max_u32_e32 v11, v16, v13
	v_min_u32_e32 v13, v16, v13
	v_max_u32_e32 v16, v15, v14
	v_min_u32_e32 v14, v15, v14
	v_max_u32_e32 v31, v33, v58
	v_min_u32_e32 v33, v33, v58
	v_max_u32_e32 v58, v20, v18
	v_min_u32_e32 v18, v20, v18
	v_max_u32_e32 v20, v22, v21
	v_min_u32_e32 v21, v22, v21
	v_max_u32_e32 v22, v24, v19
	v_min_u32_e32 v19, v24, v19
	v_max_u32_e32 v24, v23, v28
	v_min_u32_e32 v23, v23, v28
	v_max_u32_e32 v28, v25, v26
	v_min_u32_e32 v25, v25, v26
	v_max_u32_e32 v26, v30, v29
	v_min_u32_e32 v29, v30, v29
	v_max_u32_e32 v30, v32, v27
	v_min_u32_e32 v27, v32, v27
	v_max_u32_e32 v15, v17, v66
	v_min_u32_e32 v17, v17, v66
	v_max_u32_e32 v66, v4, v2
	v_min_u32_e32 v2, v4, v2
	v_max_u32_e32 v4, v6, v5
	v_min_u32_e32 v5, v6, v5
	v_max_u32_e32 v6, v8, v3
	v_min_u32_e32 v3, v8, v3
	v_max_u32_e32 v8, v7, v12
	v_min_u32_e32 v7, v7, v12
	v_max_u32_e32 v12, v9, v10
	v_min_u32_e32 v9, v9, v10
	v_max_u32_e32 v10, v14, v13
	v_min_u32_e32 v13, v14, v13
	v_max_u32_e32 v14, v16, v11
	v_min_u32_e32 v11, v16, v11
	v_max_u32_e32 v32, v31, v21
	v_min_u32_e32 v21, v31, v21
	v_max_u32_e32 v31, v33, v20
	v_min_u32_e32 v20, v33, v20
	v_max_u32_e32 v33, v58, v19
	v_min_u32_e32 v19, v58, v19
	v_max_u32_e32 v58, v18, v22
	v_min_u32_e32 v18, v18, v22
	v_max_u32_e32 v22, v29, v24
	v_min_u32_e32 v24, v29, v24
	v_max_u32_e32 v29, v26, v23
	v_min_u32_e32 v23, v26, v23
	v_max_u32_e32 v26, v27, v28
	v_min_u32_e32 v27, v27, v28
	v_max_u32_e32 v28, v30, v25
	v_min_u32_e32 v25, v30, v25
	v_max_u32_e32 v16, v15, v5
	v_min_u32_e32 v5, v15, v5
	v_max_u32_e32 v15, v17, v4
	v_min_u32_e32 v4, v17, v4
	v_max_u32_e32 v17, v66, v3
	v_min_u32_e32 v3, v66, v3
	v_max_u32_e32 v66, v2, v6
	v_min_u32_e32 v2, v2, v6
	v_max_u32_e32 v6, v13, v8
	v_min_u32_e32 v8, v13, v8
	v_max_u32_e32 v13, v10, v7
	v_min_u32_e32 v7, v10, v7
	v_max_u32_e32 v10, v11, v12
	v_min_u32_e32 v11, v11, v12
	v_max_u32_e32 v12, v14, v9
	v_min_u32_e32 v9, v14, v9
	v_max_u32_e32 v30, v32, v33
	v_min_u32_e32 v32, v32, v33
	v_max_u32_e32 v33, v31, v58
	v_min_u32_e32 v31, v31, v58
	v_max_u32_e32 v58, v21, v19
	v_min_u32_e32 v19, v21, v19
	v_max_u32_e32 v21, v20, v18
	v_min_u32_e32 v18, v20, v18
	v_max_u32_e32 v20, v27, v24
	v_min_u32_e32 v24, v27, v24
	v_max_u32_e32 v27, v25, v23
	v_min_u32_e32 v23, v25, v23
	v_max_u32_e32 v25, v26, v22
	v_min_u32_e32 v22, v26, v22
	v_max_u32_e32 v26, v28, v29
	v_min_u32_e32 v28, v28, v29
	v_max_u32_e32 v14, v16, v17
	v_min_u32_e32 v16, v16, v17
	v_max_u32_e32 v17, v15, v66
	v_min_u32_e32 v15, v15, v66
	v_max_u32_e32 v66, v5, v3
	v_min_u32_e32 v3, v5, v3
	v_max_u32_e32 v5, v4, v2
	v_min_u32_e32 v2, v4, v2
	v_max_u32_e32 v4, v11, v8
	v_min_u32_e32 v8, v11, v8
	v_max_u32_e32 v11, v9, v7
	v_min_u32_e32 v7, v9, v7
	v_max_u32_e32 v9, v10, v6
	v_min_u32_e32 v6, v10, v6
	v_max_u32_e32 v10, v12, v13
	v_min_u32_e32 v12, v12, v13
	v_max_u32_e32 v29, v30, v33
	v_min_u32_e32 v30, v30, v33
	v_max_u32_e32 v33, v32, v31
	v_min_u32_e32 v31, v32, v31
	v_max_u32_e32 v32, v58, v21
	v_min_u32_e32 v21, v58, v21
	v_max_u32_e32 v58, v19, v18
	v_min_u32_e32 v18, v19, v18
	v_max_u32_e32 v19, v23, v24
	v_min_u32_e32 v23, v23, v24
	v_max_u32_e32 v24, v27, v20
	v_min_u32_e32 v20, v27, v20
	v_max_u32_e32 v27, v28, v22
	v_min_u32_e32 v22, v28, v22
	v_max_u32_e32 v28, v26, v25
	v_min_u32_e32 v25, v26, v25
	v_max_u32_e32 v13, v14, v17
	v_min_u32_e32 v14, v14, v17
	v_max_u32_e32 v17, v16, v15
	v_min_u32_e32 v15, v16, v15
	v_max_u32_e32 v16, v66, v5
	v_min_u32_e32 v5, v66, v5
	v_max_u32_e32 v66, v3, v2
	v_min_u32_e32 v2, v3, v2
	v_max_u32_e32 v3, v7, v8
	v_min_u32_e32 v7, v7, v8
	v_max_u32_e32 v8, v11, v4
	v_min_u32_e32 v4, v11, v4
	v_max_u32_e32 v11, v12, v6
	v_min_u32_e32 v6, v12, v6
	v_max_u32_e32 v12, v10, v9
	v_min_u32_e32 v9, v10, v9
	v_max_u32_e32 v26, v29, v23
	v_min_u32_e32 v23, v29, v23
	v_max_u32_e32 v29, v30, v19
	v_min_u32_e32 v19, v30, v19
	v_max_u32_e32 v30, v33, v20
	v_min_u32_e32 v20, v33, v20
	v_max_u32_e32 v33, v31, v24
	v_min_u32_e32 v24, v31, v24
	v_max_u32_e32 v31, v32, v22
	v_min_u32_e32 v22, v32, v22
	v_max_u32_e32 v32, v21, v27
	v_min_u32_e32 v21, v21, v27
	v_max_u32_e32 v27, v58, v25
	v_min_u32_e32 v25, v58, v25
	v_max_u32_e32 v58, v18, v28
	v_min_u32_e32 v18, v18, v28
	v_max_u32_e32 v10, v13, v7
	v_min_u32_e32 v7, v13, v7
	v_max_u32_e32 v13, v14, v3
	v_min_u32_e32 v3, v14, v3
	v_max_u32_e32 v14, v17, v4
	v_min_u32_e32 v4, v17, v4
	v_max_u32_e32 v17, v15, v8
	v_min_u32_e32 v8, v15, v8
	v_max_u32_e32 v15, v16, v6
	v_min_u32_e32 v6, v16, v6
	v_max_u32_e32 v16, v5, v11
	v_min_u32_e32 v5, v5, v11
	v_max_u32_e32 v11, v66, v9
	v_min_u32_e32 v9, v66, v9
	v_max_u32_e32 v66, v2, v12
	v_min_u32_e32 v2, v2, v12
	v_max_u32_e32 v28, v26, v31
	v_min_u32_e32 v26, v26, v31
	v_max_u32_e32 v31, v29, v32
	v_min_u32_e32 v29, v29, v32
	v_max_u32_e32 v32, v30, v27
	v_min_u32_e32 v27, v30, v27
	v_max_u32_e32 v30, v33, v58
	v_min_u32_e32 v33, v33, v58
	v_max_u32_e32 v58, v23, v22
	v_min_u32_e32 v22, v23, v22
	v_max_u32_e32 v23, v19, v21
	v_min_u32_e32 v19, v19, v21
	v_max_u32_e32 v21, v20, v25
	v_min_u32_e32 v20, v20, v25
	v_max_u32_e32 v25, v24, v18
	v_min_u32_e32 v18, v24, v18
	v_max_u32_e32 v12, v10, v15
	v_min_u32_e32 v10, v10, v15
	v_max_u32_e32 v15, v13, v16
	v_min_u32_e32 v13, v13, v16
	v_max_u32_e32 v16, v14, v11
	v_min_u32_e32 v11, v14, v11
	v_max_u32_e32 v14, v17, v66
	v_min_u32_e32 v17, v17, v66
	v_max_u32_e32 v66, v7, v6
	v_min_u32_e32 v6, v7, v6
	v_max_u32_e32 v7, v3, v5
	v_min_u32_e32 v3, v3, v5
	v_max_u32_e32 v5, v4, v9
	v_min_u32_e32 v4, v4, v9
	v_max_u32_e32 v9, v8, v2
	v_min_u32_e32 v2, v8, v2
	v_min_u32_e32 v67, v60, v62
	v_min_u32_e32 v71, v53, v55
	v_min_u32_e32 v72, v57, v54
	v_min_u32_e32 v73, v52, v50
	v_min_u32_e32 v80, v41, v38
	v_max_u32_e32 v24, v28, v32
	v_min_u32_e32 v28, v28, v32
	v_max_u32_e32 v32, v31, v30
	v_min_u32_e32 v30, v31, v30
	v_max_u32_e32 v31, v26, v27
	v_min_u32_e32 v26, v26, v27
	v_max_u32_e32 v27, v29, v33
	v_min_u32_e32 v29, v29, v33
	v_max_u32_e32 v33, v58, v21
	v_min_u32_e32 v21, v58, v21
	v_max_u32_e32 v58, v23, v25
	v_min_u32_e32 v23, v23, v25
	v_max_u32_e32 v25, v22, v20
	v_min_u32_e32 v20, v22, v20
	v_max_u32_e32 v22, v19, v18
	v_min_u32_e32 v18, v19, v18
	v_max_u32_e32 v8, v12, v16
	v_min_u32_e32 v12, v12, v16
	v_max_u32_e32 v16, v15, v14
	v_min_u32_e32 v14, v15, v14
	v_max_u32_e32 v15, v10, v11
	v_min_u32_e32 v10, v10, v11
	v_max_u32_e32 v11, v13, v17
	v_min_u32_e32 v13, v13, v17
	v_max_u32_e32 v17, v66, v5
	v_min_u32_e32 v5, v66, v5
	v_max_u32_e32 v66, v7, v9
	v_min_u32_e32 v7, v7, v9
	v_max_u32_e32 v9, v6, v4
	v_min_u32_e32 v4, v6, v4
	v_max_u32_e32 v6, v3, v2
	v_min_u32_e32 v2, v3, v2
	v_min_u32_e32 v35, v40, v48
	v_min_u32_e32 v75, v44, v46
	v_min_u32_e32 v76, v47, v43
	v_max3_u32 v56, v56, v64, v81
	v_max3_u32 v36, v60, v62, v80
	v_max3_u32 v38, v67, v41, v38
	v_max3_u32 v41, v63, v59, v79
	v_max3_u32 v49, v69, v49, v74
	v_max3_u32 v42, v70, v42, v45
	v_max3_u32 v43, v71, v47, v43
	v_max3_u32 v44, v72, v44, v46
	v_max3_u32 v40, v73, v40, v48
	v_min_u32_e32 v19, v24, v32
	v_min_u32_e32 v59, v28, v30
	v_min_u32_e32 v60, v31, v27
	v_min_u32_e32 v61, v26, v29
	v_min_u32_e32 v62, v33, v58
	v_min_u32_e32 v63, v21, v23
	v_min_u32_e32 v64, v25, v22
	v_min_u32_e32 v65, v20, v18
	v_min_u32_e32 v3, v8, v16
	v_min_u32_e32 v67, v12, v14
	v_min_u32_e32 v68, v15, v11
	v_min_u32_e32 v69, v10, v13
	v_min_u32_e32 v70, v17, v66
	v_min_u32_e32 v71, v5, v7
	v_min_u32_e32 v72, v9, v6
	v_min_u32_e32 v73, v4, v2
	v_max3_u32 v45, v53, v55, v76
	v_max3_u32 v47, v57, v54, v75
	v_max3_u32 v35, v52, v50, v35
	v_max3_u32 v24, v24, v32, v73
	v_max3_u32 v2, v19, v4, v2
	v_max3_u32 v4, v28, v30, v72
	v_max3_u32 v6, v59, v9, v6
	v_max3_u32 v9, v31, v27, v71
	v_max3_u32 v5, v60, v5, v7
	v_max3_u32 v7, v26, v29, v70
	v_max3_u32 v17, v61, v17, v66
	v_max3_u32 v19, v33, v58, v69
	v_max3_u32 v10, v62, v10, v13
	v_max3_u32 v13, v21, v23, v68
	v_max3_u32 v11, v63, v15, v11
	v_max3_u32 v15, v25, v22, v67
	v_max3_u32 v12, v64, v12, v14
	v_max3_u32 v3, v20, v18, v3
	v_max3_u32 v8, v65, v8, v16
	v_max_u32_e32 v46, v56, v51
	v_min_u32_e32 v48, v56, v51
	v_max_u32_e32 v50, v34, v42
	v_min_u32_e32 v34, v34, v42
	v_max_u32_e32 v42, v36, v45
	v_min_u32_e32 v36, v36, v45
	v_max_u32_e32 v45, v38, v43
	v_min_u32_e32 v38, v38, v43
	v_max_u32_e32 v43, v41, v47
	v_min_u32_e32 v41, v41, v47
	v_max_u32_e32 v47, v37, v44
	v_min_u32_e32 v37, v37, v44
	v_max_u32_e32 v44, v39, v35
	v_min_u32_e32 v35, v39, v35
	v_max_u32_e32 v39, v49, v40
	v_min_u32_e32 v40, v49, v40
	v_max_u32_e32 v14, v24, v19
	v_min_u32_e32 v16, v24, v19
	v_max_u32_e32 v18, v2, v10
	v_min_u32_e32 v2, v2, v10
	v_max_u32_e32 v10, v4, v13
	v_min_u32_e32 v4, v4, v13
	v_max_u32_e32 v13, v6, v11
	v_min_u32_e32 v6, v6, v11
	v_max_u32_e32 v11, v9, v15
	v_min_u32_e32 v9, v9, v15
	v_max_u32_e32 v15, v5, v12
	v_min_u32_e32 v5, v5, v12
	v_max_u32_e32 v12, v7, v3
	v_min_u32_e32 v3, v7, v3
	v_max_u32_e32 v7, v17, v8
	v_min_u32_e32 v8, v17, v8
	v_max_u32_e32 v49, v46, v43
	v_min_u32_e32 v43, v46, v43
	v_max_u32_e32 v46, v50, v47
	v_min_u32_e32 v47, v50, v47
	v_max_u32_e32 v50, v42, v44
	v_min_u32_e32 v42, v42, v44
	v_max_u32_e32 v44, v45, v39
	v_min_u32_e32 v39, v45, v39
	v_max_u32_e32 v45, v48, v41
	v_min_u32_e32 v41, v48, v41
	v_max_u32_e32 v48, v34, v37
	v_min_u32_e32 v34, v34, v37
	v_max_u32_e32 v37, v36, v35
	v_min_u32_e32 v35, v36, v35
	v_max_u32_e32 v36, v38, v40
	v_min_u32_e32 v38, v38, v40
	v_max_u32_e32 v17, v14, v11
	v_min_u32_e32 v11, v14, v11
	v_max_u32_e32 v14, v18, v15
	v_min_u32_e32 v15, v18, v15
	v_max_u32_e32 v18, v10, v12
	v_min_u32_e32 v10, v10, v12
	v_max_u32_e32 v12, v13, v7
	v_min_u32_e32 v7, v13, v7
	v_max_u32_e32 v13, v16, v9
	v_min_u32_e32 v9, v16, v9
	v_max_u32_e32 v16, v2, v5
	v_min_u32_e32 v2, v2, v5
	v_max_u32_e32 v5, v4, v3
	v_min_u32_e32 v3, v4, v3
	v_max_u32_e32 v4, v6, v8
	v_min_u32_e32 v6, v6, v8
	v_max_u32_e32 v40, v49, v50
	v_min_u32_e32 v49, v49, v50
	v_max_u32_e32 v50, v46, v44
	v_min_u32_e32 v44, v46, v44
	v_max_u32_e32 v46, v43, v42
	v_min_u32_e32 v42, v43, v42
	v_max_u32_e32 v43, v47, v39
	v_min_u32_e32 v39, v47, v39
	v_max_u32_e32 v47, v45, v37
	v_min_u32_e32 v37, v45, v37
	v_max_u32_e32 v45, v48, v36
	v_min_u32_e32 v36, v48, v36
	v_max_u32_e32 v48, v41, v35
	v_min_u32_e32 v35, v41, v35
	v_max_u32_e32 v41, v34, v38
	v_min_u32_e32 v34, v34, v38
	v_max_u32_e32 v8, v17, v18
	v_min_u32_e32 v17, v17, v18
	v_max_u32_e32 v18, v14, v12
	v_min_u32_e32 v12, v14, v12
	v_max_u32_e32 v14, v11, v10
	v_min_u32_e32 v10, v11, v10
	v_max_u32_e32 v11, v15, v7
	v_min_u32_e32 v7, v15, v7
	v_max_u32_e32 v15, v13, v5
	v_min_u32_e32 v5, v13, v5
	v_max_u32_e32 v13, v16, v4
	v_min_u32_e32 v4, v16, v4
	v_max_u32_e32 v16, v9, v3
	v_min_u32_e32 v3, v9, v3
	v_max_u32_e32 v9, v2, v6
	v_min_u32_e32 v2, v2, v6
	v_min_u32_e32 v38, v40, v50
	v_min_u32_e32 v51, v49, v44
	v_min_u32_e32 v52, v46, v43
	v_min_u32_e32 v53, v42, v39
	v_min_u32_e32 v54, v47, v45
	v_min_u32_e32 v55, v37, v36
	v_min_u32_e32 v56, v48, v41
	v_min_u32_e32 v57, v35, v34
	v_min_u32_e32 v6, v8, v18
	v_min_u32_e32 v19, v17, v12
	v_min_u32_e32 v20, v14, v11
	v_min_u32_e32 v21, v10, v7
	v_min_u32_e32 v22, v15, v13
	v_min_u32_e32 v23, v5, v4
	v_min_u32_e32 v24, v16, v9
	v_min_u32_e32 v25, v3, v2
	v_max3_u32 v25, v40, v50, v25
	v_max3_u32 v8, v57, v8, v18
	v_max3_u32 v2, v38, v3, v2
	v_max3_u32 v3, v35, v34, v6
	v_max3_u32 v6, v49, v44, v24
	v_max3_u32 v12, v56, v17, v12
	v_max3_u32 v9, v51, v16, v9
	v_max3_u32 v16, v48, v41, v19
	v_max3_u32 v17, v46, v43, v23
	v_max3_u32 v11, v55, v14, v11
	v_max3_u32 v4, v52, v5, v4
	v_max3_u32 v5, v37, v36, v20
	v_max3_u32 v14, v42, v39, v22
	v_max3_u32 v7, v54, v10, v7
	v_max3_u32 v10, v53, v15, v13
	v_max3_u32 v13, v47, v45, v21
	v_max_u32_e32 v15, v25, v13
	v_min_u32_e32 v13, v25, v13
	v_max_u32_e32 v18, v2, v7
	v_min_u32_e32 v2, v2, v7
	v_max_u32_e32 v7, v6, v5
	v_min_u32_e32 v5, v6, v5
	v_max_u32_e32 v6, v9, v11
	v_min_u32_e32 v9, v9, v11
	v_max_u32_e32 v11, v17, v16
	v_min_u32_e32 v16, v17, v16
	v_max_u32_e32 v17, v4, v12
	v_min_u32_e32 v4, v4, v12
	v_max_u32_e32 v12, v14, v3
	v_min_u32_e32 v3, v14, v3
	v_max_u32_e32 v14, v10, v8
	v_min_u32_e32 v8, v10, v8
	v_max_u32_e32 v10, v15, v11
	v_min_u32_e32 v11, v15, v11
	v_max_u32_e32 v15, v18, v17
	v_min_u32_e32 v17, v18, v17
	v_max_u32_e32 v18, v7, v12
	v_min_u32_e32 v7, v7, v12
	v_max_u32_e32 v12, v6, v14
	v_min_u32_e32 v6, v6, v14
	v_max_u32_e32 v14, v13, v16
	v_min_u32_e32 v13, v13, v16
	v_max_u32_e32 v16, v2, v4
	v_min_u32_e32 v2, v2, v4
	v_max_u32_e32 v4, v5, v3
	v_min_u32_e32 v3, v5, v3
	v_max_u32_e32 v5, v9, v8
	v_min_u32_e32 v8, v9, v8
	v_max_u32_e32 v9, v10, v18
	v_min_u32_e32 v10, v10, v18
	v_max_u32_e32 v18, v15, v12
	v_min_u32_e32 v12, v15, v12
	v_max_u32_e32 v15, v11, v7
	v_min_u32_e32 v7, v11, v7
	v_max_u32_e32 v19, v17, v6
	v_min_u32_e32 v6, v17, v6
	v_max_u32_e32 v20, v14, v4
	v_min_u32_e32 v14, v14, v4
	v_max_u32_e32 v21, v16, v5
	v_min_u32_e32 v22, v16, v5
	v_max_u32_e32 v25, v13, v3
	v_min_u32_e32 v13, v13, v3
	v_max_u32_e32 v26, v2, v8
	v_min_u32_e32 v8, v2, v8
	v_max_u32_e32 v16, v9, v18
	v_min_u32_e32 v4, v9, v18
	v_max_u32_e32 v11, v10, v12
	v_min_u32_e32 v2, v10, v12
	v_max_u32_e32 v17, v15, v19
	v_min_u32_e32 v5, v15, v19
	v_max_u32_e32 v12, v7, v6
	v_min_u32_e32 v3, v7, v6
	v_max_u32_e32 v23, v20, v21
	v_min_u32_e32 v9, v20, v21
	v_max_u32_e32 v18, v14, v22
	v_min_u32_e32 v6, v14, v22
	v_max_u32_e32 v24, v25, v26
	v_min_u32_e32 v10, v25, v26
	v_max_u32_e32 v19, v13, v8
	v_min_u32_e32 v7, v13, v8
	ds_bpermute_b32 v8, v106, v16
	ds_bpermute_b32 v20, v106, v4
	ds_bpermute_b32 v14, v106, v11
	ds_bpermute_b32 v27, v106, v2
	ds_bpermute_b32 v13, v106, v17
	ds_bpermute_b32 v26, v106, v5
	ds_bpermute_b32 v21, v106, v12
	ds_bpermute_b32 v30, v106, v3
	ds_bpermute_b32 v15, v106, v23
	ds_bpermute_b32 v28, v106, v9
	ds_bpermute_b32 v25, v106, v18
	ds_bpermute_b32 v32, v106, v6
	ds_bpermute_b32 v22, v106, v24
	ds_bpermute_b32 v31, v106, v10
	ds_bpermute_b32 v29, v106, v19
	ds_bpermute_b32 v33, v106, v7
	s_and_saveexec_b64 s[12:13], vcc
	s_cbranch_execz .LBB0_1977
	s_waitcnt lgkmcnt(0)
	v_max_u32_e32 v16, v16, v33
	v_max_u32_e32 v23, v23, v30
	v_max_u32_e32 v17, v17, v32
	v_max_u32_e32 v24, v24, v27
	v_max_u32_e32 v11, v11, v31
	v_max_u32_e32 v18, v18, v26
	v_max_u32_e32 v12, v12, v28
	v_max_u32_e32 v19, v19, v20
	v_max_u32_e32 v4, v4, v29
	v_max_u32_e32 v9, v9, v21
	v_max_u32_e32 v5, v5, v25
	v_max_u32_e32 v10, v10, v14
	v_max_u32_e32 v2, v2, v22
	v_max_u32_e32 v6, v6, v13
	v_max_u32_e32 v3, v3, v15
	v_max_u32_e32 v7, v7, v8
	v_min_u32_e32 v30, v16, v23
	v_min_u32_e32 v27, v17, v24
	v_min_u32_e32 v26, v11, v18
	v_min_u32_e32 v20, v12, v19
	v_min_u32_e32 v21, v4, v9
	v_min_u32_e32 v14, v5, v10
	v_min_u32_e32 v13, v2, v6
	v_min_u32_e32 v8, v3, v7
	v_min_u32_e32 v32, v30, v27
	v_min_u32_e32 v28, v26, v20
	v_min_u32_e32 v25, v21, v14
	v_min_u32_e32 v15, v13, v8
	v_max_u32_e32 v27, v30, v27
	v_max_u32_e32 v20, v26, v20
	v_max_u32_e32 v14, v21, v14
	v_max_u32_e32 v8, v13, v8
	v_min_u32_e32 v26, v27, v20
	v_min_u32_e32 v13, v14, v8
	v_min_u32_e32 v21, v26, v13
	v_max_u32_e32 v26, v26, v13
	v_max_u32_e32 v13, v27, v20
	v_max_u32_e32 v8, v14, v8
	v_min_u32_e32 v14, v13, v8
	v_max_u32_e32 v8, v13, v8
	v_max_u32_e32 v13, v16, v23
	v_max_u32_e32 v16, v17, v24
	v_max_u32_e32 v11, v11, v18
	v_max_u32_e32 v12, v12, v19
	v_max_u32_e32 v4, v4, v9
	v_max_u32_e32 v5, v5, v10
	v_max_u32_e32 v2, v2, v6
	v_max_u32_e32 v3, v3, v7
	v_min_u32_e32 v17, v13, v16
	v_min_u32_e32 v18, v11, v12
	v_min_u32_e32 v9, v4, v5
	v_min_u32_e32 v6, v2, v3
	v_min_u32_e32 v7, v9, v6
	v_max_u32_e32 v10, v17, v18
	v_max_u32_e32 v6, v9, v6
	v_min_u32_e32 v19, v17, v18
	v_min_u32_e32 v9, v10, v6
	v_max_u32_e32 v17, v10, v6
	v_max_u32_e32 v6, v13, v16
	v_max_u32_e32 v10, v11, v12
	v_max_u32_e32 v4, v4, v5
	v_max_u32_e32 v2, v2, v3
	v_min_u32_e32 v11, v6, v10
	v_min_u32_e32 v3, v4, v2
	v_min_u32_e32 v16, v11, v3
	v_max_u32_e32 v5, v11, v3
	v_max_u32_e32 v3, v6, v10
	v_max_u32_e32 v2, v4, v2
	v_min_u32_e32 v4, v3, v2
	v_max_u32_e32 v6, v3, v2
	v_mov_b32_e32 v2, v107
	v_cmp_gt_i32_e64 s[0:1], 0, v6
	v_add_u32_e32 v2, v2, v109
	v_ashrrev_i32_e32 v3, 31, v2
	v_lshlrev_b64 v[10:11], 8, v[2:3]
	v_and_b32_e32 v2, 0x7fffff80, v6
	v_bitop3_b32 v3, v6, s17, v6 bitop3:0xcf
	v_cndmask_b32_e64 v2, v3, v2, s[0:1]
	v_and_b32_e32 v3, 0x7fffff80, v4
	v_bitop3_b32 v18, v4, s17, v4 bitop3:0xcf
	v_cmp_gt_i32_e64 s[0:1], 0, v4
	v_lshlrev_b32_e32 v4, 8, v4
	v_min_u32_e32 v20, v19, v7
	v_max_u32_e32 v7, v19, v7
	v_cndmask_b32_e64 v3, v18, v3, s[0:1]
	v_and_b32_e32 v18, 0x7f00, v4
	v_and_b32_e32 v4, 0x7fffff80, v5
	v_bitop3_b32 v19, v5, s17, v5 bitop3:0xcf
	v_cmp_gt_i32_e64 s[0:1], 0, v5
	v_lshlrev_b32_e32 v5, 16, v5
	v_and_b32_e32 v6, 0x7f, v6
	v_and_b32_e32 v5, 0x7f0000, v5
	v_or_b32_e32 v10, s14, v10
	v_cndmask_b32_e64 v4, v19, v4, s[0:1]
	v_or3_b32 v6, v18, v6, v5
	v_and_b32_e32 v5, 0x7fffff80, v16
	v_bitop3_b32 v18, v16, s17, v16 bitop3:0xcf
	v_cmp_gt_i32_e64 s[0:1], 0, v16
	v_lshl_add_u64 v[12:13], v[10:11], 2, s[6:7]
	v_lshlrev_b32_e32 v16, 24, v16
	v_cndmask_b32_e64 v5, v18, v5, s[0:1]
	global_store_dwordx4 v[12:13], v[2:5], off
	v_cmp_gt_i32_e64 s[0:1], 0, v17
	v_and_b32_e32 v16, 0x7f000000, v16
	v_and_b32_e32 v2, 0x7fffff80, v17
	v_bitop3_b32 v3, v17, s17, v17 bitop3:0xcf
	v_cndmask_b32_e64 v2, v3, v2, s[0:1]
	v_and_b32_e32 v3, 0x7fffff80, v9
	v_bitop3_b32 v4, v9, s17, v9 bitop3:0xcf
	v_cmp_gt_i32_e64 s[0:1], 0, v9
	v_bitop3_b32 v6, v6, s18, v16 bitop3:0x36
	v_bitop3_b32 v16, v7, s17, v7 bitop3:0xcf
	v_cndmask_b32_e64 v3, v4, v3, s[0:1]
	v_lshlrev_b32_e32 v4, 8, v9
	v_and_b32_e32 v9, 0x7f00, v4
	v_and_b32_e32 v4, 0x7fffff80, v7
	v_cmp_gt_i32_e64 s[0:1], 0, v7
	v_lshlrev_b32_e32 v7, 16, v7
	v_and_b32_e32 v5, 0x7f, v17
	v_and_b32_e32 v7, 0x7f0000, v7
	v_cndmask_b32_e64 v4, v16, v4, s[0:1]
	v_or3_b32 v7, v9, v5, v7
	v_and_b32_e32 v5, 0x7fffff80, v20
	v_bitop3_b32 v9, v20, s17, v20 bitop3:0xcf
	v_cmp_gt_i32_e64 s[0:1], 0, v20
	v_min_u32_e32 v31, v32, v28
	v_min_u32_e32 v22, v25, v15
	v_cndmask_b32_e64 v5, v9, v5, s[0:1]
	global_store_dwordx4 v[12:13], v[2:5], off offset:16
	v_cmp_gt_i32_e64 s[0:1], 0, v8
	v_lshlrev_b32_e32 v9, 24, v20
	v_and_b32_e32 v2, 0x7fffff80, v8
	v_bitop3_b32 v3, v8, s17, v8 bitop3:0xcf
	v_cndmask_b32_e64 v2, v3, v2, s[0:1]
	v_and_b32_e32 v3, 0x7fffff80, v14
	v_bitop3_b32 v4, v14, s17, v14 bitop3:0xcf
	v_cmp_gt_i32_e64 s[0:1], 0, v14
	v_and_b32_e32 v9, 0x7f000000, v9
	v_bitop3_b32 v7, v7, s18, v9 bitop3:0x36
	v_cndmask_b32_e64 v3, v4, v3, s[0:1]
	v_lshlrev_b32_e32 v4, 8, v14
	v_and_b32_e32 v5, 0x7f, v8
	v_and_b32_e32 v8, 0x7f00, v4
	v_and_b32_e32 v4, 0x7fffff80, v26
	v_bitop3_b32 v9, v26, s17, v26 bitop3:0xcf
	v_cmp_gt_i32_e64 s[0:1], 0, v26
	v_max_u32_e32 v28, v32, v28
	v_max_u32_e32 v15, v25, v15
	v_cndmask_b32_e64 v4, v9, v4, s[0:1]
	v_lshlrev_b32_e32 v9, 16, v26
	v_and_b32_e32 v9, 0x7f0000, v9
	v_or3_b32 v8, v8, v5, v9
	v_and_b32_e32 v5, 0x7fffff80, v21
	v_bitop3_b32 v9, v21, s17, v21 bitop3:0xcf
	v_cmp_gt_i32_e64 s[0:1], 0, v21
	v_min_u32_e32 v25, v28, v15
	v_max_u32_e32 v15, v28, v15
	v_cndmask_b32_e64 v5, v9, v5, s[0:1]
	global_store_dwordx4 v[12:13], v[2:5], off offset:32
	v_cmp_gt_i32_e64 s[0:1], 0, v15
	v_lshlrev_b32_e32 v9, 24, v21
	v_and_b32_e32 v2, 0x7fffff80, v15
	v_bitop3_b32 v3, v15, s17, v15 bitop3:0xcf
	v_cndmask_b32_e64 v2, v3, v2, s[0:1]
	v_and_b32_e32 v3, 0x7fffff80, v25
	v_bitop3_b32 v4, v25, s17, v25 bitop3:0xcf
	v_cmp_gt_i32_e64 s[0:1], 0, v25
	v_min_u32_e32 v29, v31, v22
	v_max_u32_e32 v22, v31, v22
	v_and_b32_e32 v9, 0x7f000000, v9
	v_cndmask_b32_e64 v3, v4, v3, s[0:1]
	v_lshlrev_b32_e32 v4, 8, v25
	v_bitop3_b32 v8, v8, s18, v9 bitop3:0x36
	v_and_b32_e32 v9, 0x7f00, v4
	v_and_b32_e32 v4, 0x7fffff80, v22
	v_bitop3_b32 v14, v22, s17, v22 bitop3:0xcf
	v_cmp_gt_i32_e64 s[0:1], 0, v22
	v_and_b32_e32 v5, 0x7f, v15
	s_nop 0
	v_cndmask_b32_e64 v4, v14, v4, s[0:1]
	v_lshlrev_b32_e32 v14, 16, v22
	v_and_b32_e32 v14, 0x7f0000, v14
	v_or3_b32 v9, v9, v5, v14
	v_and_b32_e32 v5, 0x7fffff80, v29
	v_bitop3_b32 v14, v29, s17, v29 bitop3:0xcf
	v_cmp_gt_i32_e64 s[0:1], 0, v29
	s_nop 1
	v_cndmask_b32_e64 v5, v14, v5, s[0:1]
	v_lshlrev_b32_e32 v14, 24, v29
	v_and_b32_e32 v14, 0x7f000000, v14
	v_bitop3_b32 v9, v9, s18, v14 bitop3:0x36
	global_store_dwordx4 v[12:13], v[2:5], off offset:48
	s_nop 1
	v_lshl_add_u64 v[2:3], s[8:9], 0, v[10:11]
	global_store_dwordx4 v[2:3], v[6:9], off
	s_branch .LBB0_1977
